# retention-output loop: decay parameters via scalar loads, tile staging waits vmcnt(4) instead of draining the output stores, epilogue gate waits no longer force the next unit's 20 prefetched tile load
# speedup vs baseline: 1.0004x; 1.0004x over previous
; __device__ __forceinline__ void retout_fetch(RetoutRegs& R, const bf16* proj, const bf16* st, int unit, int tid) {
;     const int h = unit & 7, n = (unit >> 3) & 31, b = unit >> 8;
;     const bf16* base = proj + ((size_t)b * SEQ + (size_t)n * CHUNK) * INW + h * HDIM;
;     tile_fetch(R.q, base + C_RQ, INW, tid); tile_fetch(R.k, base + C_RK, INW, tid); tile_fetch(R.v, base + C_RV, INW, tid);
;     tile_fetch(R.sf, st + ((((size_t)0 * BATCH + b) * NRH + h) * NCH + n) * (size_t)(HDIM * HDIM), HDIM, tid);
;     tile_fetch(R.sb, st + ((((size_t)1 * BATCH + b) * NRH + h) * NCH + n) * (size_t)(HDIM * HDIM), HDIM, tid);
; }
; __device__ __forceinline__ void retout_loop(ldsp lds, const bf16* proj, const bf16* st, bf16* mix, const float* ldr, int u0, int ustep, int nunits, int tid0) {
;     const ldsp TQ = lds, TK = lds + TILE_BYTES, TV = lds + 2 * TILE_BYTES, TS = lds + 3 * TILE_BYTES;
;     int tid = tid0;
;     RetoutRegs R;
;     int unit = u0;
;     if (unit < nunits) retout_fetch(R, proj, st, unit, tid);
;     ...
;         const float wf = __builtin_amdgcn_exp2f(l2f * (float)(i + 1)), wb = __builtin_amdgcn_exp2f(l2b * (float)(CHUNK - i));
; #pragma unroll
;         for (int c = 0; c < 8; ++c) acc[c] = acc[c] * wb + accF[c] * wf;
.LBB0_459:
	s_or_b64 exec, exec, s[6:7]
	s_waitcnt lgkmcnt(0)
	s_barrier
	s_getreg_b32 s0, hwreg(HW_REG_HW_ID, 0, 6)
	s_lshl_b32 s0, s0, 2
	s_and_b32 s0, s0, 0xfc
	s_add_i32 s0, s0, 0
	s_add_i32 s0, s0, 0x22240
	v_mov_b32_e32 v0, s0
	ds_read_b32 v0, v0
	v_mbcnt_lo_u32_b32 v1, -1, 0
	v_mbcnt_hi_u32_b32 v1, -1, v1
	s_waitcnt lgkmcnt(0)
	v_readfirstlane_b32 s0, v0
	s_nop 1
	v_lshl_add_u32 v170, s0, 6, v1
	v_readlane_b32 s0, v253, 46
	v_readlane_b32 s1, v253, 47
	s_andn2_b64 vcc, exec, s[0:1]
	s_cbranch_vccnz .LBB0_464
	v_lshlrev_b32_e32 v0, 4, v170
	v_readlane_b32 s0, v253, 48
	v_and_b32_e32 v16, 0xf0, v0
	v_readlane_b32 s1, v253, 49
	v_add_u32_e32 v2, 0x200, v170
	v_add_u32_e32 v10, 0x400, v170
	v_add_u32_e32 v12, 0x600, v170
	v_lshl_add_u64 v[8:9], s[0:1], 0, v[16:17]
	s_waitcnt vmcnt(11)
	v_ashrrev_i32_e32 v50, 4, v170
	v_ashrrev_i32_e32 v52, 4, v2
	s_waitcnt vmcnt(9)
	v_ashrrev_i32_e32 v58, 4, v10
	v_ashrrev_i32_e32 v60, 4, v12
	v_mad_i64_i32 v[0:1], s[0:1], v50, s85, v[8:9]
	v_mad_i64_i32 v[4:5], s[0:1], v52, s85, v[8:9]
	v_mad_i64_i32 v[10:11], s[0:1], v58, s85, v[8:9]
	v_mad_i64_i32 v[12:13], s[0:1], v60, s85, v[8:9]
	v_readlane_b32 s0, v253, 50
	v_readlane_b32 s1, v253, 51
	v_ashrrev_i32_e32 v51, 31, v50
	v_ashrrev_i32_e32 v53, 31, v52
	v_lshl_add_u64 v[26:27], s[0:1], 0, v[16:17]
	v_mad_i64_i32 v[18:19], s[0:1], v50, s85, v[26:27]
	v_mad_i64_i32 v[22:23], s[0:1], v52, s85, v[26:27]
	v_mad_i64_i32 v[28:29], s[0:1], v58, s85, v[26:27]
	v_mad_i64_i32 v[30:31], s[0:1], v60, s85, v[26:27]
	v_readlane_b32 s0, v253, 52
	v_readlane_b32 s1, v253, 53
	v_ashrrev_i32_e32 v59, 31, v58
	v_ashrrev_i32_e32 v61, 31, v60
	v_lshl_add_u64 v[42:43], s[0:1], 0, v[16:17]
	v_mad_i64_i32 v[34:35], s[0:1], v50, s85, v[42:43]
	v_mad_i64_i32 v[38:39], s[0:1], v52, s85, v[42:43]
	v_mad_i64_i32 v[44:45], s[0:1], v58, s85, v[42:43]
	v_mad_i64_i32 v[46:47], s[0:1], v60, s85, v[42:43]
	v_readlane_b32 s0, v253, 54
	v_readlane_b32 s1, v253, 55
	v_lshlrev_b64 v[66:67], 8, v[50:51]
	v_lshlrev_b64 v[68:69], 8, v[52:53]
	s_waitcnt vmcnt(8)
	v_lshl_add_u64 v[62:63], s[0:1], 0, v[16:17]
	v_readlane_b32 s0, v253, 56
	v_readlane_b32 s1, v253, 57
	v_lshlrev_b64 v[74:75], 8, v[58:59]
	v_lshlrev_b64 v[76:77], 8, v[60:61]
	s_waitcnt vmcnt(7)
	v_lshl_add_u64 v[78:79], s[0:1], 0, v[16:17]
	v_lshl_add_u64 v[50:51], v[62:63], 0, v[66:67]
	v_lshl_add_u64 v[54:55], v[62:63], 0, v[68:69]
	v_lshl_add_u64 v[58:59], v[62:63], 0, v[74:75]
	v_lshl_add_u64 v[62:63], v[62:63], 0, v[76:77]
	v_lshl_add_u64 v[66:67], v[78:79], 0, v[66:67]
	v_lshl_add_u64 v[70:71], v[78:79], 0, v[68:69]
	v_lshl_add_u64 v[74:75], v[78:79], 0, v[74:75]
	v_lshl_add_u64 v[78:79], v[78:79], 0, v[76:77]
	global_load_dwordx4 v[0:3], v[0:1], off
	s_nop 0
	global_load_dwordx4 v[4:7], v[4:5], off
	s_nop 0
	global_load_dwordx4 v[8:11], v[10:11], off
	s_nop 0
	global_load_dwordx4 v[12:15], v[12:13], off
	s_nop 0
	global_load_dwordx4 v[18:21], v[18:19], off
	s_nop 0
	global_load_dwordx4 v[22:25], v[22:23], off
	s_nop 0
	global_load_dwordx4 v[26:29], v[28:29], off
	s_nop 0
	global_load_dwordx4 v[30:33], v[30:31], off
	s_nop 0
	global_load_dwordx4 v[34:37], v[34:35], off
	s_nop 0
	global_load_dwordx4 v[38:41], v[38:39], off
	s_nop 0
	global_load_dwordx4 v[42:45], v[44:45], off
	s_nop 0
	global_load_dwordx4 v[46:49], v[46:47], off
	s_nop 0
	global_load_dwordx4 v[50:53], v[50:51], off
	s_nop 0
	global_load_dwordx4 v[54:57], v[54:55], off
	s_nop 0
	global_load_dwordx4 v[58:61], v[58:59], off
	s_nop 0
	global_load_dwordx4 v[62:65], v[62:63], off
	s_nop 0
	global_load_dwordx4 v[66:69], v[66:67], off
	s_nop 0
	global_load_dwordx4 v[70:73], v[70:71], off
	s_nop 0
	global_load_dwordx4 v[74:77], v[74:75], off
	s_nop 0
	global_load_dwordx4 v[78:81], v[78:79], off
	v_xor_b32_e32 v16, 16, v233
	v_cmp_lt_i32_e32 vcc, v16, v235
	v_readlane_b32 s0, v254, 45
	v_readlane_b32 s1, v253, 0
	v_cndmask_b32_e32 v16, v233, v16, vcc
	v_lshlrev_b32_e32 v171, 2, v16
	v_xor_b32_e32 v16, 32, v233
	v_cmp_lt_i32_e32 vcc, v16, v235
	s_nop 1
	v_cndmask_b32_e32 v16, v233, v16, vcc
	v_lshlrev_b32_e32 v172, 2, v16
	s_waitcnt vmcnt(0)
	s_branch .LBB0_462
.LBB0_461:
	v_sub_u32_e32 v16, 0x80, v174
	v_cvt_f32_i32_e32 v16, v16
	v_add_u32_e32 v162, 1, v174
	v_cvt_f32_i32_e32 v162, v162
	v_and_b32_e32 v165, 63, v170
	v_mul_f32_e32 v16, v177, v16
	v_exp_f32_e32 v16, v16
	v_mul_f32_e32 v162, v175, v162
	v_exp_f32_e32 v166, v162
	v_or_b32_e32 v164, 4, v178
	v_pk_mul_f32 v[152:153], v[16:17], v[152:153] op_sel_hi:[0,1]
	v_pk_mul_f32 v[150:151], v[16:17], v[150:151] op_sel_hi:[0,1]
	v_pk_mul_f32 v[132:133], v[16:17], v[132:133] op_sel_hi:[0,1]
	v_pk_mul_f32 v[130:131], v[16:17], v[130:131] op_sel_hi:[0,1]
	v_pk_fma_f32 v[116:117], v[166:167], v[116:117], v[152:153] op_sel_hi:[0,1,1]
	v_pk_fma_f32 v[114:115], v[166:167], v[114:115], v[150:151] op_sel_hi:[0,1,1]
	v_pk_mul_f32 v[150:151], v[16:17], v[156:157] op_sel_hi:[0,1]
	v_pk_mul_f32 v[152:153], v[16:17], v[154:155] op_sel_hi:[0,1]
	v_pk_mul_f32 v[148:149], v[16:17], v[148:149] op_sel_hi:[0,1]
	v_pk_mul_f32 v[146:147], v[16:17], v[146:147] op_sel_hi:[0,1]
	v_pk_mul_f32 v[144:145], v[16:17], v[144:145] op_sel_hi:[0,1]
	v_pk_mul_f32 v[142:143], v[16:17], v[142:143] op_sel_hi:[0,1]
	v_pk_mul_f32 v[140:141], v[16:17], v[140:141] op_sel_hi:[0,1]
	v_pk_mul_f32 v[138:139], v[16:17], v[138:139] op_sel_hi:[0,1]
	v_pk_mul_f32 v[136:137], v[16:17], v[136:137] op_sel_hi:[0,1]
	v_pk_mul_f32 v[134:135], v[16:17], v[134:135] op_sel_hi:[0,1]
	v_pk_fma_f32 v[100:101], v[166:167], v[100:101], v[132:133] op_sel_hi:[0,1,1]
	v_pk_fma_f32 v[98:99], v[166:167], v[98:99], v[130:131] op_sel_hi:[0,1,1]
	v_pk_mul_f32 v[130:131], v[16:17], v[160:161] op_sel_hi:[0,1]
; template <bool A_TR, bool B_TR>
; __device__ __forceinline__ void mm128(f32x4 (&acc)[8], ldsp TA, ldsp TB, int w, int lane) {
;     ...
;     for (int ks = 0; ks < 4; ++ks) {
;         const bf16x8 a = A_TR ? frag_tr(ab, 0, ks) : frag_row(ab, 0, ks);
; #pragma unroll
;         for (int c = 0; c < 8; ++c) {
;             const bf16x8 b = B_TR ? frag_tr(bb, c, ks) : frag_row(bb, c, ks);
;             acc[c] = __builtin_amdgcn_mfma_f32_16x16x32_bf16(b, a, acc[c], 0, 0, 0);
;         }
;     }
; __device__ __forceinline__ void retout_loop(ldsp lds, const bf16* proj, const bf16* st, bf16* mix, const float* ldr, int u0, int ustep, int nunits, int tid0) {
;     ...
;         const float wf = __builtin_amdgcn_exp2f(l2f * (float)(i + 1)), wb = __builtin_amdgcn_exp2f(l2b * (float)(CHUNK - i));
; #pragma unroll
;         for (int c = 0; c < 8; ++c) acc[c] = acc[c] * wb + accF[c] * wf;
;         asm volatile("" ::: "memory");
;         if (unext < nunits) retout_fetch(R, proj, st, unext, tid);
;         mm128<false, true>(acc, TK, TV, w, lane);
	v_pk_mul_f32 v[132:133], v[16:17], v[158:159] op_sel_hi:[0,1]
	v_bfe_u32 v16, v170, 2, 2
	v_pk_fma_f32 v[128:129], v[166:167], v[128:129], v[130:131] op_sel_hi:[0,1,1]
	v_and_or_b32 v16, v180, 24, v16
	v_lshlrev_b32_e32 v130, 3, v165
	v_mul_u32_u24_e32 v16, 0x110, v16
	v_and_b32_e32 v130, 24, v130
	v_or_b32_e32 v163, 8, v178
	v_or_b32_e32 v162, 12, v178
	v_pk_fma_f32 v[124:125], v[166:167], v[124:125], v[150:151] op_sel_hi:[0,1,1]
	v_pk_fma_f32 v[122:123], v[166:167], v[122:123], v[152:153] op_sel_hi:[0,1,1]
	v_pk_fma_f32 v[120:121], v[166:167], v[120:121], v[148:149] op_sel_hi:[0,1,1]
	v_pk_fma_f32 v[118:119], v[166:167], v[118:119], v[146:147] op_sel_hi:[0,1,1]
	v_pk_fma_f32 v[112:113], v[166:167], v[112:113], v[144:145] op_sel_hi:[0,1,1]
	v_pk_fma_f32 v[110:111], v[166:167], v[110:111], v[142:143] op_sel_hi:[0,1,1]
	v_pk_fma_f32 v[108:109], v[166:167], v[108:109], v[140:141] op_sel_hi:[0,1,1]
	v_pk_fma_f32 v[106:107], v[166:167], v[106:107], v[138:139] op_sel_hi:[0,1,1]
	v_pk_fma_f32 v[104:105], v[166:167], v[104:105], v[136:137] op_sel_hi:[0,1,1]
	v_pk_fma_f32 v[102:103], v[166:167], v[102:103], v[134:135] op_sel_hi:[0,1,1]
	v_pk_fma_f32 v[126:127], v[166:167], v[126:127], v[132:133] op_sel_hi:[0,1,1]
	v_add3_u32 v16, s33, v16, v130
	s_setprio 1
	ds_read_b128 v[180:183], v176 offset:34816
	ds_read_b64_tr_b16 v[186:187], v16 offset:1088
	ds_read_b64_tr_b16 v[184:185], v16
	ds_read_b64_tr_b16 v[188:189], v16 offset:64
	ds_read_b64_tr_b16 v[190:191], v16 offset:1152
	ds_read_b64_tr_b16 v[192:193], v16 offset:96
	ds_read_b64_tr_b16 v[194:195], v16 offset:1184
	ds_read_b64_tr_b16 v[196:197], v16 offset:128
	ds_read_b64_tr_b16 v[198:199], v16 offset:1216
	ds_read_b64_tr_b16 v[200:201], v16 offset:160
	ds_read_b64_tr_b16 v[202:203], v16 offset:1248
	ds_read_b64_tr_b16 v[204:205], v16 offset:192
	ds_read_b64_tr_b16 v[206:207], v16 offset:1280
	ds_read_b64_tr_b16 v[212:213], v16 offset:32
	ds_read_b64_tr_b16 v[214:215], v16 offset:1120
	ds_read_b64_tr_b16 v[216:217], v16 offset:224
	ds_read_b64_tr_b16 v[218:219], v16 offset:1312
	s_waitcnt lgkmcnt(14)
	v_mfma_f32_16x16x32_bf16 v[114:117], v[184:187], v[180:183], v[114:117]
	ds_read_b128 v[220:223], v176 offset:34880
	s_waitcnt lgkmcnt(13)
	v_mfma_f32_16x16x32_bf16 v[118:121], v[188:191], v[180:183], v[118:121]
	ds_read_b64_tr_b16 v[236:237], v16 offset:8704
	ds_read_b64_tr_b16 v[238:239], v16 offset:9792
	s_waitcnt lgkmcnt(13)
	v_mfma_f32_16x16x32_bf16 v[110:113], v[192:195], v[180:183], v[110:113]
	ds_read_b64_tr_b16 v[184:185], v16 offset:8736
	ds_read_b64_tr_b16 v[186:187], v16 offset:9824
	s_waitcnt lgkmcnt(13)
	v_mfma_f32_16x16x32_bf16 v[106:109], v[196:199], v[180:183], v[106:109]
	ds_read_b64_tr_b16 v[188:189], v16 offset:8768
	ds_read_b64_tr_b16 v[190:191], v16 offset:9856
	s_waitcnt lgkmcnt(13)
	v_mfma_f32_16x16x32_bf16 v[102:105], v[200:203], v[180:183], v[102:105]
	ds_read_b64_tr_b16 v[192:193], v16 offset:8800
	ds_read_b64_tr_b16 v[194:195], v16 offset:9888
	s_waitcnt lgkmcnt(13)
	v_mfma_f32_16x16x32_bf16 v[98:101], v[204:207], v[180:183], v[98:101]
	ds_read_b64_tr_b16 v[196:197], v16 offset:8832
	ds_read_b64_tr_b16 v[198:199], v16 offset:9920
	s_waitcnt lgkmcnt(13)
	v_mfma_f32_16x16x32_bf16 v[122:125], v[212:215], v[180:183], v[122:125]
	ds_read_b64_tr_b16 v[200:201], v16 offset:8864
	ds_read_b64_tr_b16 v[202:203], v16 offset:9952
	s_waitcnt lgkmcnt(13)
	v_mfma_f32_16x16x32_bf16 v[126:129], v[216:219], v[180:183], v[126:129]
	ds_read_b64_tr_b16 v[204:205], v16 offset:8896
	ds_read_b64_tr_b16 v[206:207], v16 offset:9984
	ds_read_b64_tr_b16 v[212:213], v16 offset:8928
	ds_read_b64_tr_b16 v[214:215], v16 offset:10016
	s_waitcnt lgkmcnt(14)
	v_mfma_f32_16x16x32_bf16 v[114:117], v[236:239], v[220:223], v[114:117]
	ds_read_b128 v[216:219], v176 offset:34944
	s_waitcnt lgkmcnt(13)
	v_mfma_f32_16x16x32_bf16 v[122:125], v[184:187], v[220:223], v[122:125]
	ds_read_b64_tr_b16 v[180:181], v16 offset:17408
	ds_read_b64_tr_b16 v[182:183], v16 offset:18496
	s_waitcnt lgkmcnt(13)
	v_mfma_f32_16x16x32_bf16 v[118:121], v[188:191], v[220:223], v[118:121]
	ds_read_b64_tr_b16 v[236:237], v16 offset:17440
	ds_read_b64_tr_b16 v[238:239], v16 offset:18528
	s_waitcnt lgkmcnt(13)
	v_mfma_f32_16x16x32_bf16 v[110:113], v[192:195], v[220:223], v[110:113]
	ds_read_b64_tr_b16 v[184:185], v16 offset:17472
	ds_read_b64_tr_b16 v[186:187], v16 offset:18560
	s_waitcnt lgkmcnt(13)
	v_mfma_f32_16x16x32_bf16 v[106:109], v[196:199], v[220:223], v[106:109]
	ds_read_b64_tr_b16 v[188:189], v16 offset:17504
	ds_read_b64_tr_b16 v[190:191], v16 offset:18592
	s_waitcnt lgkmcnt(13)
	v_mfma_f32_16x16x32_bf16 v[102:105], v[200:203], v[220:223], v[102:105]
	ds_read_b64_tr_b16 v[192:193], v16 offset:17536
	ds_read_b64_tr_b16 v[194:195], v16 offset:18624
	s_waitcnt lgkmcnt(13)
	v_mfma_f32_16x16x32_bf16 v[98:101], v[204:207], v[220:223], v[98:101]
	ds_read_b64_tr_b16 v[196:197], v16 offset:17568
	ds_read_b64_tr_b16 v[198:199], v16 offset:18656
	s_waitcnt lgkmcnt(13)
	v_mfma_f32_16x16x32_bf16 v[126:129], v[212:215], v[220:223], v[126:129]
	ds_read_b64_tr_b16 v[200:201], v16 offset:17600
	ds_read_b64_tr_b16 v[202:203], v16 offset:18688
	ds_read_b64_tr_b16 v[204:205], v16 offset:17632
	ds_read_b64_tr_b16 v[206:207], v16 offset:18720
	s_waitcnt lgkmcnt(14)
	v_mfma_f32_16x16x32_bf16 v[114:117], v[180:183], v[216:219], v[114:117]
	ds_read_b128 v[212:215], v176 offset:35008
	s_waitcnt lgkmcnt(13)
	v_mfma_f32_16x16x32_bf16 v[122:125], v[236:239], v[216:219], v[122:125]
	ds_read_b64_tr_b16 v[220:221], v16 offset:26112
	ds_read_b64_tr_b16 v[222:223], v16 offset:27200
	s_waitcnt lgkmcnt(13)
; __device__ __forceinline__ void retout_loop(ldsp lds, const bf16* proj, const bf16* st, bf16* mix, const float* ldr, int u0, int ustep, int nunits, int tid0) {
;     ...
;         mm128<false, true>(acc, TK, TV, w, lane);
;         float ss = 0.f;
; #pragma unroll
;         for (int c = 0; c < 8; ++c) ss += (acc[c][0] * acc[c][0] + acc[c][1] * acc[c][1]) + (acc[c][2] * acc[c][2] + acc[c][3] * acc[c][3]);
;         ss += __shfl_xor(ss, 16); ss += __shfl_xor(ss, 32);
;         const float rn = rsqrtf(ss * (1.f / 128.f) + NORM_EPS);
; #pragma unroll
;         for (int c = 0; c < 8; ++c) acc[c] = acc[c] * rn;
;         store_acc_tile(TK, acc, w, lane);
	v_mfma_f32_16x16x32_bf16 v[118:121], v[184:187], v[216:219], v[118:121]
	ds_read_b64_tr_b16 v[180:181], v16 offset:26144
	ds_read_b64_tr_b16 v[182:183], v16 offset:27232
	s_waitcnt lgkmcnt(13)
	v_mfma_f32_16x16x32_bf16 v[110:113], v[188:191], v[216:219], v[110:113]
	ds_read_b64_tr_b16 v[236:237], v16 offset:26176
	ds_read_b64_tr_b16 v[238:239], v16 offset:27264
	s_waitcnt lgkmcnt(13)
	v_mfma_f32_16x16x32_bf16 v[106:109], v[192:195], v[216:219], v[106:109]
	ds_read_b64_tr_b16 v[184:185], v16 offset:26208
	ds_read_b64_tr_b16 v[186:187], v16 offset:27296
	s_waitcnt lgkmcnt(13)
	v_mfma_f32_16x16x32_bf16 v[102:105], v[196:199], v[216:219], v[102:105]
	ds_read_b64_tr_b16 v[188:189], v16 offset:26240
	ds_read_b64_tr_b16 v[190:191], v16 offset:27328
	s_waitcnt lgkmcnt(13)
	v_mfma_f32_16x16x32_bf16 v[98:101], v[200:203], v[216:219], v[98:101]
	ds_read_b64_tr_b16 v[192:193], v16 offset:26272
	ds_read_b64_tr_b16 v[194:195], v16 offset:27360
	s_waitcnt lgkmcnt(13)
	v_mfma_f32_16x16x32_bf16 v[126:129], v[204:207], v[216:219], v[126:129]
	ds_read_b64_tr_b16 v[196:197], v16 offset:26304
	ds_read_b64_tr_b16 v[198:199], v16 offset:27392
	ds_read_b64_tr_b16 v[200:201], v16 offset:26336
	ds_read_b64_tr_b16 v[202:203], v16 offset:27424
	s_waitcnt lgkmcnt(14)
	v_mfma_f32_16x16x32_bf16 v[114:117], v[220:223], v[212:215], v[114:117]
	s_waitcnt lgkmcnt(12)
	v_mfma_f32_16x16x32_bf16 v[122:125], v[180:183], v[212:215], v[122:125]
	s_waitcnt lgkmcnt(10)
	v_mfma_f32_16x16x32_bf16 v[118:121], v[236:239], v[212:215], v[118:121]
	s_waitcnt lgkmcnt(8)
	v_mfma_f32_16x16x32_bf16 v[110:113], v[184:187], v[212:215], v[110:113]
	s_waitcnt lgkmcnt(6)
	v_mfma_f32_16x16x32_bf16 v[106:109], v[188:191], v[212:215], v[106:109]
	s_waitcnt lgkmcnt(4)
	v_mfma_f32_16x16x32_bf16 v[102:105], v[192:195], v[212:215], v[102:105]
	s_waitcnt lgkmcnt(2)
	v_mfma_f32_16x16x32_bf16 v[98:101], v[196:199], v[212:215], v[98:101]
	s_waitcnt lgkmcnt(0)
	v_mfma_f32_16x16x32_bf16 v[126:129], v[200:203], v[212:215], v[126:129]
	s_nop 7
	s_setprio 0
	v_mov_b32_e32 v132, v115
	v_mov_b32_e32 v133, v123
	v_mov_b32_e32 v130, v114
	v_mov_b32_e32 v131, v122
	v_pk_mul_f32 v[132:133], v[132:133], v[132:133]
	v_mov_b32_e32 v134, v117
	v_mov_b32_e32 v135, v125
	v_pk_fma_f32 v[130:131], v[130:131], v[130:131], v[132:133]
	v_mov_b32_e32 v132, v116
	v_mov_b32_e32 v133, v124
	v_pk_mul_f32 v[134:135], v[134:135], v[134:135]
	v_mul_f32_e32 v16, v106, v106
	v_pk_fma_f32 v[132:133], v[132:133], v[132:133], v[134:135]
	v_pk_mul_f32 v[134:135], v[118:119], v[118:119]
	v_pk_add_f32 v[130:131], v[130:131], v[132:133]
	v_pk_mul_f32 v[132:133], v[120:121], v[120:121]
	v_pk_add_f32 v[130:131], v[130:131], v[130:131] op_sel:[0,1] op_sel_hi:[1,0]
	v_pk_mov_b32 v[136:137], v[134:135], v[132:133] op_sel:[1,0]
	v_mov_b32_e32 v135, v133
	v_pk_add_f32 v[132:133], v[136:137], v[134:135]
	v_mul_f32_e32 v134, v107, v107
	v_pk_add_f32 v[132:133], v[132:133], v[132:133] op_sel:[0,1] op_sel_hi:[1,0]
	v_mov_b32_e32 v131, v16
	v_mov_b32_e32 v133, v134
	v_mul_f32_e32 v16, v111, v111
	v_mul_f32_e32 v135, v108, v108
	v_pk_add_f32 v[130:131], v[130:131], v[132:133]
	v_pk_fma_f32 v[132:133], v[110:111], v[110:111], v[16:17] op_sel_hi:[1,1,0]
	v_mul_f32_e32 v16, v113, v113
	v_mul_f32_e32 v136, v109, v109
	v_mov_b32_e32 v133, v135
	v_pk_fma_f32 v[134:135], v[112:113], v[112:113], v[16:17] op_sel_hi:[1,1,0]
	v_mul_f32_e32 v16, v126, v126
	v_mov_b32_e32 v135, v136
	v_pk_add_f32 v[132:133], v[132:133], v[134:135]
	v_pk_mul_f32 v[134:135], v[102:103], v[102:103]
	v_pk_add_f32 v[130:131], v[130:131], v[132:133]
	v_pk_mul_f32 v[132:133], v[104:105], v[104:105]
	v_pk_add_f32 v[130:131], v[130:131], v[130:131] op_sel:[0,1] op_sel_hi:[1,0]
	v_pk_mov_b32 v[136:137], v[134:135], v[132:133] op_sel:[1,0]
	v_mov_b32_e32 v135, v133
	v_pk_add_f32 v[132:133], v[136:137], v[134:135]
	v_mul_f32_e32 v134, v127, v127
	v_pk_add_f32 v[132:133], v[132:133], v[132:133] op_sel:[0,1] op_sel_hi:[1,0]
	v_mov_b32_e32 v131, v16
	v_mov_b32_e32 v133, v134
	v_mul_f32_e32 v16, v99, v99
	v_mul_f32_e32 v135, v128, v128
	v_pk_add_f32 v[130:131], v[130:131], v[132:133]
	v_pk_fma_f32 v[132:133], v[98:99], v[98:99], v[16:17] op_sel_hi:[1,1,0]
	v_mul_f32_e32 v16, v101, v101
	v_mul_f32_e32 v136, v129, v129
	v_mov_b32_e32 v133, v135
	v_pk_fma_f32 v[134:135], v[100:101], v[100:101], v[16:17] op_sel_hi:[1,1,0]
	s_mov_b32 s5, 0x800000
	v_mov_b32_e32 v135, v136
	v_pk_add_f32 v[132:133], v[132:133], v[134:135]
	s_lshl_b64 s[8:9], s[8:9], 13
	v_pk_add_f32 v[130:131], v[130:131], v[132:133]
	s_nop 0
	v_add_f32_e32 v16, v130, v131
	ds_bpermute_b32 v130, v171, v16
	s_waitcnt lgkmcnt(0)
	v_add_f32_e32 v16, v16, v130
	ds_bpermute_b32 v130, v172, v16
	s_waitcnt lgkmcnt(0)
	v_add_f32_e32 v16, v16, v130
	v_fmamk_f32 v16, v16, 0x3c000000, v234
	v_mul_f32_e32 v130, 0x4b800000, v16
	v_cmp_gt_f32_e32 vcc, s5, v16
	s_add_u32 s5, s60, s8
	s_addc_u32 s9, s61, s9
	v_cndmask_b32_e32 v16, v16, v130, vcc
	v_rsq_f32_e32 v16, v16
	s_lshl_b32 s8, s10, 1
	s_add_u32 s8, s5, s8
	s_addc_u32 s9, s9, 0
	v_mul_f32_e32 v130, 0x45800000, v16
	v_cndmask_b32_e32 v16, v16, v130, vcc
	v_pk_mul_f32 v[108:109], v[108:109], v[16:17] op_sel_hi:[1,0]
	v_pk_mul_f32 v[106:107], v[106:107], v[16:17] op_sel_hi:[1,0]
	v_pk_mul_f32 v[100:101], v[100:101], v[16:17] op_sel_hi:[1,0]
	v_pk_mul_f32 v[98:99], v[98:99], v[16:17] op_sel_hi:[1,0]
	v_pk_mul_f32 v[128:129], v[128:129], v[16:17] op_sel_hi:[1,0]
	v_pk_mul_f32 v[126:127], v[126:127], v[16:17] op_sel_hi:[1,0]
	v_cvt_pk_bf16_f32 v106, v106, v107
	v_cvt_pk_bf16_f32 v107, v108, v109
	v_cvt_pk_bf16_f32 v98, v98, v99
	v_cvt_pk_bf16_f32 v99, v100, v101
	v_cvt_pk_bf16_f32 v100, v126, v127
	v_cvt_pk_bf16_f32 v101, v128, v129
	s_cmp_eq_u64 s[6:7], 0
	s_cbranch_scc1 .Lro_w0
	s_waitcnt vmcnt(3)
; __device__ __forceinline__ unsigned cvt_pk_bf16(float lo, float hi) { const f32x2c_t v = {lo, hi}; return __builtin_bit_cast(unsigned, __builtin_convertvector(v, bf16x2c_t)); }
; #define LAS __attribute__((address_space(3)))
; #define LDS_WAIT() asm volatile("s_waitcnt lgkmcnt(0)" ::: "memory")
; __device__ __forceinline__ float bf_lo(unsigned w) { return __uint_as_float(w << 16); }
; __device__ __forceinline__ float bf_hi(unsigned w) { return __uint_as_float(w & 0xffff0000u); }
; __device__ __forceinline__ void store_acc_tile(ldsp T, const f32x4 (&a)[8], int w, int lane) {
;     const unsigned fr = lane & 15, fq = lane >> 4, row = 16u * w + fr;
; #pragma unroll
;     for (int c = 0; c < 8; ++c) { v2u v; v[0] = cvt_pk_bf16(a[c][0], a[c][1]); v[1] = cvt_pk_bf16(a[c][2], a[c][3]);
;         *(LAS v2u*)(T + offb(row, 2u * c + (fq >> 1)) + 8u * (fq & 1)) = v; }
; }
; __device__ __forceinline__ void retout_loop(ldsp lds, const bf16* proj, const bf16* st, bf16* mix, const float* ldr, int u0, int ustep, int nunits, int tid0) {
;     ...
;         for (int c = 0; c < 8; ++c) acc[c] = acc[c] * rn;
;         store_acc_tile(TK, acc, w, lane);
;         LDS_WAIT();
;         bf16* obase = mix + (row0 + 16 * w) * DM + MIX_R + h * HDIM;
; #pragma unroll
;         for (int k = 0; k < 4; ++k) { const int q = lane + 64 * k, r = q >> 4, ch = q & 15;
;             const v4u s = *(const LAS v4u*)(TK + offb(16 * w + r, ch)), gw = gr[k];
;             v4u o;
; #pragma unroll
;             for (int e = 0; e < 4; ++e) { const float g0 = bf_lo(gw[e]), g1 = bf_hi(gw[e]);
;                 o[e] = cvt_pk_bf16(g0 / (1.f + __expf(-g0)) * bf_lo(s[e]), g1 / (1.f + __expf(-g1)) * bf_hi(s[e])); }
;             *(v4u*)(obase + (size_t)r * DM + 8 * ch) = o; }
.Lro_w0:
	s_waitcnt vmcnt(23)
	v_lshlrev_b32_e32 v109, 16, v94
	v_and_b32_e32 v94, 0xffff0000, v94
	ds_write2_b64 v179, v[98:99], v[100:101] offset0:24 offset1:28
	v_mul_f32_e32 v98, 0xbfb8aa3b, v109
	v_mul_f32_e32 v99, 0xbfb8aa3b, v94
	v_exp_f32_e32 v98, v98
	v_exp_f32_e32 v99, v99
	v_pk_mul_f32 v[116:117], v[116:117], v[16:17] op_sel_hi:[1,0]
	v_pk_mul_f32 v[114:115], v[114:115], v[16:17] op_sel_hi:[1,0]
	v_pk_mul_f32 v[124:125], v[124:125], v[16:17] op_sel_hi:[1,0]
	v_pk_mul_f32 v[122:123], v[122:123], v[16:17] op_sel_hi:[1,0]
	v_pk_mul_f32 v[120:121], v[120:121], v[16:17] op_sel_hi:[1,0]
	v_pk_mul_f32 v[118:119], v[118:119], v[16:17] op_sel_hi:[1,0]
	v_pk_mul_f32 v[112:113], v[112:113], v[16:17] op_sel_hi:[1,0]
	v_pk_mul_f32 v[110:111], v[110:111], v[16:17] op_sel_hi:[1,0]
	v_pk_mul_f32 v[104:105], v[104:105], v[16:17] op_sel_hi:[1,0]
	v_pk_mul_f32 v[102:103], v[102:103], v[16:17] op_sel_hi:[1,0]
	v_cvt_pk_bf16_f32 v114, v114, v115
	v_cvt_pk_bf16_f32 v115, v116, v117
	v_cvt_pk_bf16_f32 v116, v122, v123
	v_cvt_pk_bf16_f32 v117, v124, v125
	ds_write2_b64 v179, v[114:115], v[116:117] offset1:4
	v_cvt_pk_bf16_f32 v114, v118, v119
	v_cvt_pk_bf16_f32 v115, v120, v121
	v_cvt_pk_bf16_f32 v110, v110, v111
	v_cvt_pk_bf16_f32 v111, v112, v113
	v_cvt_pk_bf16_f32 v102, v102, v103
	v_cvt_pk_bf16_f32 v103, v104, v105
	v_lshlrev_b32_e32 v16, 4, v173
	v_pk_add_f32 v[98:99], v[98:99], 1.0 op_sel_hi:[1,0]
	ds_write2_b64 v179, v[114:115], v[110:111] offset0:8 offset1:12
	ds_write2_b64 v179, v[106:107], v[102:103] offset0:16 offset1:20
	v_lshl_add_u64 v[106:107], s[8:9], 0, v[16:17]
	v_div_scale_f32 v110, s[8:9], v99, v99, v94
	v_rcp_f32_e32 v111, v110
	v_add_u32_e32 v108, 0, v16
	v_or_b32_e32 v16, s4, v178
	v_mad_u64_u32 v[100:101], s[8:9], v16, s47, v[108:109]
	v_fma_f32 v16, -v110, v111, 1.0
	s_waitcnt lgkmcnt(0)
	v_fmac_f32_e32 v111, v16, v111
	v_div_scale_f32 v16, vcc, v94, v99, v94
	ds_read_b128 v[102:105], v100 offset:34816
	v_mul_f32_e32 v100, v16, v111
	v_fma_f32 v101, -v110, v100, v16
	v_fmac_f32_e32 v100, v101, v111
	v_div_scale_f32 v101, s[8:9], v98, v98, v109
	v_fma_f32 v16, -v110, v100, v16
	v_rcp_f32_e32 v110, v101
	v_div_fmas_f32 v16, v16, v111, v100
	v_div_fixup_f32 v111, v16, v99, v94
	s_waitcnt lgkmcnt(0)
	v_lshlrev_b32_e32 v112, 16, v102
	v_fma_f32 v16, -v101, v110, 1.0
	v_fmac_f32_e32 v110, v16, v110
	v_div_scale_f32 v16, vcc, v109, v98, v109
	v_mul_f32_e32 v94, v16, v110
	v_fma_f32 v99, -v101, v94, v16
	v_fmac_f32_e32 v94, v99, v110
	v_fma_f32 v16, -v101, v94, v16
	v_div_fmas_f32 v16, v16, v110, v94
	v_div_fixup_f32 v110, v16, v98, v109
	v_lshlrev_b32_e32 v16, 16, v95
	v_and_b32_e32 v109, 0xffff0000, v95
	v_mul_f32_e32 v94, 0xbfb8aa3b, v16
	v_mul_f32_e32 v95, 0xbfb8aa3b, v109
	v_exp_f32_e32 v94, v94
	v_exp_f32_e32 v95, v95
	v_and_b32_e32 v113, 0xffff0000, v102
	v_or_b32_e32 v98, s4, v164
	v_mad_u64_u32 v[98:99], s[8:9], v98, s47, v[108:109]
	v_pk_add_f32 v[114:115], v[94:95], 1.0 op_sel_hi:[1,0]
	v_pk_mul_f32 v[94:95], v[110:111], v[112:113]
	v_div_scale_f32 v116, s[8:9], v115, v115, v109
	v_rcp_f32_e32 v117, v116
	v_cvt_pk_bf16_f32 v94, v94, v95
	ds_read_b128 v[98:101], v98 offset:34816
	v_fma_f32 v95, -v116, v117, 1.0
	v_fmac_f32_e32 v117, v95, v117
	v_div_scale_f32 v95, vcc, v109, v115, v109
	v_mul_f32_e32 v102, v95, v117
	v_fma_f32 v110, -v116, v102, v95
	v_fmac_f32_e32 v102, v110, v117
	v_div_scale_f32 v110, s[8:9], v114, v114, v16
	v_fma_f32 v95, -v116, v102, v95
	v_rcp_f32_e32 v116, v110
	v_div_fmas_f32 v95, v95, v117, v102
	v_div_fixup_f32 v111, v95, v115, v109
	v_and_b32_e32 v115, 0xffff0000, v97
	v_fma_f32 v95, -v110, v116, 1.0
	v_fmac_f32_e32 v116, v95, v116
	v_div_scale_f32 v95, vcc, v16, v114, v16
	v_mul_f32_e32 v102, v95, v116
	v_fma_f32 v109, -v110, v102, v95
	v_fmac_f32_e32 v102, v109, v116
	v_lshlrev_b32_e32 v109, 16, v96
	v_fma_f32 v95, -v110, v102, v95
	v_and_b32_e32 v96, 0xffff0000, v96
	v_mul_f32_e32 v110, 0xbfb8aa3b, v109
	v_exp_f32_e32 v112, v110
	v_mul_f32_e32 v110, 0xbfb8aa3b, v96
	v_exp_f32_e32 v113, v110
	v_div_fmas_f32 v95, v95, v116, v102
	v_div_fixup_f32 v110, v95, v114, v16
	v_lshlrev_b32_e32 v102, 16, v103
	v_pk_add_f32 v[112:113], v[112:113], 1.0 op_sel_hi:[1,0]
	v_and_b32_e32 v103, 0xffff0000, v103
	v_div_scale_f32 v16, s[8:9], v113, v113, v96
	v_rcp_f32_e32 v114, v16
	v_pk_mul_f32 v[102:103], v[110:111], v[102:103]
	s_nop 0
	v_cvt_pk_bf16_f32 v95, v102, v103
	v_fma_f32 v102, -v16, v114, 1.0
	v_fmac_f32_e32 v114, v102, v114
	v_div_scale_f32 v102, vcc, v96, v113, v96
	v_mul_f32_e32 v103, v102, v114
	v_fma_f32 v110, -v16, v103, v102
	v_fmac_f32_e32 v103, v110, v114
	v_fma_f32 v16, -v16, v103, v102
	v_div_scale_f32 v102, s[8:9], v112, v112, v109
	v_rcp_f32_e32 v110, v102
	v_div_fmas_f32 v16, v16, v114, v103
	v_div_fixup_f32 v103, v16, v113, v96
	v_lshlrev_b32_e32 v114, 16, v97
	v_fma_f32 v16, -v102, v110, 1.0
	v_fmac_f32_e32 v110, v16, v110
	v_div_scale_f32 v16, vcc, v109, v112, v109
	v_mul_f32_e32 v111, v16, v110
	v_fma_f32 v96, -v102, v111, v16
	v_fmac_f32_e32 v111, v96, v110
	v_mul_f32_e32 v96, 0xbfb8aa3b, v114
	v_mul_f32_e32 v97, 0xbfb8aa3b, v115
	v_exp_f32_e32 v96, v96
	v_exp_f32_e32 v97, v97
	v_fma_f32 v16, -v102, v111, v16
	v_div_fmas_f32 v16, v16, v110, v111
	v_div_fixup_f32 v102, v16, v112, v109
	v_pk_add_f32 v[112:113], v[96:97], 1.0 op_sel_hi:[1,0]
	v_lshlrev_b32_e32 v110, 16, v104
	v_div_scale_f32 v16, s[8:9], v113, v113, v115
	v_rcp_f32_e32 v109, v16
	v_and_b32_e32 v111, 0xffff0000, v104
	v_pk_mul_f32 v[96:97], v[102:103], v[110:111]
	s_nop 0
	v_cvt_pk_bf16_f32 v96, v96, v97
	v_fma_f32 v97, -v16, v109, 1.0
	v_fmac_f32_e32 v109, v97, v109
	v_div_scale_f32 v97, vcc, v115, v113, v115
	v_mul_f32_e32 v102, v97, v109
	v_fma_f32 v103, -v16, v102, v97
	v_fmac_f32_e32 v102, v103, v109
	v_fma_f32 v16, -v16, v102, v97
	v_div_scale_f32 v97, s[8:9], v112, v112, v114
	v_rcp_f32_e32 v104, v97
	v_div_fmas_f32 v16, v16, v109, v102
	v_div_fixup_f32 v103, v16, v113, v115
	v_fma_f32 v16, -v97, v104, 1.0
	v_fmac_f32_e32 v104, v16, v104
	v_div_scale_f32 v16, vcc, v114, v112, v114
	v_mul_f32_e32 v102, v16, v104
	v_fma_f32 v109, -v97, v102, v16
	v_fmac_f32_e32 v102, v109, v104
	v_fma_f32 v16, -v97, v102, v16
	v_div_fmas_f32 v16, v16, v104, v102
	s_cmp_eq_u64 s[6:7], 0
	s_cbranch_scc1 .Lro_w1
	s_waitcnt vmcnt(2)
; __device__ __forceinline__ unsigned cvt_pk_bf16(float lo, float hi) { const f32x2c_t v = {lo, hi}; return __builtin_bit_cast(unsigned, __builtin_convertvector(v, bf16x2c_t)); }
; #define LAS __attribute__((address_space(3)))
; #define LDS_WAIT() asm volatile("s_waitcnt lgkmcnt(0)" ::: "memory")
; __device__ __forceinline__ float bf_lo(unsigned w) { return __uint_as_float(w << 16); }
; __device__ __forceinline__ float bf_hi(unsigned w) { return __uint_as_float(w & 0xffff0000u); }
; __device__ __forceinline__ void retout_loop(ldsp lds, const bf16* proj, const bf16* st, bf16* mix, const float* ldr, int u0, int ustep, int nunits, int tid0) {
;     ...
;         LDS_WAIT();
;         bf16* obase = mix + (row0 + 16 * w) * DM + MIX_R + h * HDIM;
; #pragma unroll
;         for (int k = 0; k < 4; ++k) { const int q = lane + 64 * k, r = q >> 4, ch = q & 15;
;             const v4u s = *(const LAS v4u*)(TK + offb(16 * w + r, ch)), gw = gr[k];
;             v4u o;
; #pragma unroll
;             for (int e = 0; e < 4; ++e) { const float g0 = bf_lo(gw[e]), g1 = bf_hi(gw[e]);
;                 o[e] = cvt_pk_bf16(g0 / (1.f + __expf(-g0)) * bf_lo(s[e]), g1 / (1.f + __expf(-g1)) * bf_hi(s[e])); }
;             *(v4u*)(obase + (size_t)r * DM + 8 * ch) = o; }
.Lro_w1:
	s_waitcnt vmcnt(22)
	v_lshlrev_b32_e32 v109, 16, v90
	v_div_fixup_f32 v102, v16, v112, v114
	v_and_b32_e32 v90, 0xffff0000, v90
	v_mul_f32_e32 v16, 0xbfb8aa3b, v109
	v_exp_f32_e32 v110, v16
	v_mul_f32_e32 v16, 0xbfb8aa3b, v90
	v_exp_f32_e32 v111, v16
	v_lshlrev_b32_e32 v104, 16, v105
	v_and_b32_e32 v105, 0xffff0000, v105
	v_pk_mul_f32 v[102:103], v[102:103], v[104:105]
	v_lshlrev_b32_e32 v16, 13, v178
	v_cvt_pk_bf16_f32 v97, v102, v103
	v_pk_add_f32 v[102:103], v[110:111], 1.0 op_sel_hi:[1,0]
	v_lshl_add_u64 v[104:105], v[106:107], 0, v[16:17]
	v_div_scale_f32 v110, s[8:9], v103, v103, v90
	v_rcp_f32_e32 v111, v110
	global_store_dwordx4 v[104:105], v[94:97], off offset:2048
	v_lshlrev_b32_e32 v104, 16, v91
	v_and_b32_e32 v105, 0xffff0000, v91
	v_fma_f32 v16, -v110, v111, 1.0
	v_fmac_f32_e32 v111, v16, v111
	v_div_scale_f32 v16, vcc, v90, v103, v90
	v_mul_f32_e32 v94, v16, v111
	v_div_scale_f32 v96, s[8:9], v102, v102, v109
	v_fma_f32 v95, -v110, v94, v16
	v_rcp_f32_e32 v97, v96
	v_fmac_f32_e32 v94, v95, v111
	v_fma_f32 v16, -v110, v94, v16
	v_div_fmas_f32 v16, v16, v111, v94
	v_div_fixup_f32 v95, v16, v103, v90
	v_fma_f32 v16, -v96, v97, 1.0
	v_fmac_f32_e32 v97, v16, v97
	v_div_scale_f32 v16, vcc, v109, v102, v109
	v_mul_f32_e32 v94, v16, v97
	v_fma_f32 v90, -v96, v94, v16
	v_fmac_f32_e32 v94, v90, v97
	v_mul_f32_e32 v90, 0xbfb8aa3b, v104
	v_mul_f32_e32 v91, 0xbfb8aa3b, v105
	v_exp_f32_e32 v90, v90
	v_exp_f32_e32 v91, v91
	v_fma_f32 v16, -v96, v94, v16
	v_div_fmas_f32 v16, v16, v97, v94
	v_div_fixup_f32 v94, v16, v102, v109
	v_pk_add_f32 v[102:103], v[90:91], 1.0 op_sel_hi:[1,0]
	s_waitcnt lgkmcnt(0)
	v_lshlrev_b32_e32 v96, 16, v98
	v_div_scale_f32 v16, s[8:9], v103, v103, v105
	v_rcp_f32_e32 v109, v16
	v_and_b32_e32 v97, 0xffff0000, v98
	v_pk_mul_f32 v[90:91], v[94:95], v[96:97]
	s_nop 0
	v_cvt_pk_bf16_f32 v90, v90, v91
	v_fma_f32 v91, -v16, v109, 1.0
	v_fmac_f32_e32 v109, v91, v109
	v_div_scale_f32 v91, vcc, v105, v103, v105
	v_mul_f32_e32 v94, v91, v109
	v_fma_f32 v95, -v16, v94, v91
	v_fmac_f32_e32 v94, v95, v109
	v_fma_f32 v16, -v16, v94, v91
	v_div_scale_f32 v91, s[8:9], v102, v102, v104
	v_rcp_f32_e32 v98, v91
	v_div_fmas_f32 v16, v16, v109, v94
	v_div_fixup_f32 v95, v16, v103, v105
	v_lshlrev_b32_e32 v103, 16, v92
	v_fma_f32 v16, -v91, v98, 1.0
	v_fmac_f32_e32 v98, v16, v98
	v_div_scale_f32 v16, vcc, v104, v102, v104
	v_mul_f32_e32 v94, v16, v98
	v_fma_f32 v96, -v91, v94, v16
	v_fmac_f32_e32 v94, v96, v98
	v_fma_f32 v16, -v91, v94, v16
	v_and_b32_e32 v92, 0xffff0000, v92
	v_mul_f32_e32 v91, 0xbfb8aa3b, v103
	v_exp_f32_e32 v96, v91
	v_mul_f32_e32 v91, 0xbfb8aa3b, v92
	v_exp_f32_e32 v97, v91
	v_div_fmas_f32 v16, v16, v98, v94
	v_div_fixup_f32 v94, v16, v102, v104
	v_lshlrev_b32_e32 v98, 16, v99
	v_pk_add_f32 v[96:97], v[96:97], 1.0 op_sel_hi:[1,0]
	v_and_b32_e32 v99, 0xffff0000, v99
	v_div_scale_f32 v16, s[8:9], v97, v97, v92
	v_rcp_f32_e32 v102, v16
	v_pk_mul_f32 v[94:95], v[94:95], v[98:99]
	v_and_b32_e32 v104, 0xffff0000, v93
	v_cvt_pk_bf16_f32 v91, v94, v95
	v_fma_f32 v94, -v16, v102, 1.0
	v_fmac_f32_e32 v102, v94, v102
	v_div_scale_f32 v94, vcc, v92, v97, v92
	v_mul_f32_e32 v95, v94, v102
	v_fma_f32 v98, -v16, v95, v94
	v_fmac_f32_e32 v95, v98, v102
	v_fma_f32 v16, -v16, v95, v94
	v_div_scale_f32 v94, s[8:9], v96, v96, v103
	v_rcp_f32_e32 v98, v94
	v_div_fmas_f32 v16, v16, v102, v95
	v_div_fixup_f32 v95, v16, v97, v92
	v_lshlrev_b32_e32 v102, 16, v93
	v_fma_f32 v16, -v94, v98, 1.0
	v_fmac_f32_e32 v98, v16, v98
	v_div_scale_f32 v16, vcc, v103, v96, v103
	v_mul_f32_e32 v97, v16, v98
	v_fma_f32 v92, -v94, v97, v16
	v_fmac_f32_e32 v97, v92, v98
	v_mul_f32_e32 v92, 0xbfb8aa3b, v102
	v_mul_f32_e32 v93, 0xbfb8aa3b, v104
	v_exp_f32_e32 v92, v92
	v_exp_f32_e32 v93, v93
	v_fma_f32 v16, -v94, v97, v16
	v_div_fmas_f32 v16, v16, v98, v97
	v_div_fixup_f32 v94, v16, v96, v103
	v_pk_add_f32 v[98:99], v[92:93], 1.0 op_sel_hi:[1,0]
	v_lshlrev_b32_e32 v96, 16, v100
	v_div_scale_f32 v16, s[8:9], v99, v99, v104
	v_rcp_f32_e32 v103, v16
	v_and_b32_e32 v97, 0xffff0000, v100
	v_pk_mul_f32 v[92:93], v[94:95], v[96:97]
	s_nop 0
	v_cvt_pk_bf16_f32 v92, v92, v93
	v_fma_f32 v93, -v16, v103, 1.0
	v_fmac_f32_e32 v103, v93, v103
	v_div_scale_f32 v93, vcc, v104, v99, v104
	v_mul_f32_e32 v94, v93, v103
	v_fma_f32 v95, -v16, v94, v93
	v_fmac_f32_e32 v94, v95, v103
	v_fma_f32 v16, -v16, v94, v93
	v_div_scale_f32 v93, s[8:9], v98, v98, v102
	v_rcp_f32_e32 v96, v93
	v_div_fmas_f32 v16, v16, v103, v94
	v_div_fixup_f32 v95, v16, v99, v104
	s_cmp_eq_u64 s[6:7], 0
	s_cbranch_scc1 .Lro_w2
	s_waitcnt vmcnt(2)
; __device__ __forceinline__ unsigned cvt_pk_bf16(float lo, float hi) { const f32x2c_t v = {lo, hi}; return __builtin_bit_cast(unsigned, __builtin_convertvector(v, bf16x2c_t)); }
; #define LAS __attribute__((address_space(3)))
; #define LDS_WAIT() asm volatile("s_waitcnt lgkmcnt(0)" ::: "memory")
; __device__ __forceinline__ float bf_lo(unsigned w) { return __uint_as_float(w << 16); }
; __device__ __forceinline__ float bf_hi(unsigned w) { return __uint_as_float(w & 0xffff0000u); }
; __device__ __forceinline__ void retout_loop(ldsp lds, const bf16* proj, const bf16* st, bf16* mix, const float* ldr, int u0, int ustep, int nunits, int tid0) {
;     ...
;         LDS_WAIT();
;         bf16* obase = mix + (row0 + 16 * w) * DM + MIX_R + h * HDIM;
; #pragma unroll
;         for (int k = 0; k < 4; ++k) { const int q = lane + 64 * k, r = q >> 4, ch = q & 15;
;             const v4u s = *(const LAS v4u*)(TK + offb(16 * w + r, ch)), gw = gr[k];
;             v4u o;
; #pragma unroll
;             for (int e = 0; e < 4; ++e) { const float g0 = bf_lo(gw[e]), g1 = bf_hi(gw[e]);
;                 o[e] = cvt_pk_bf16(g0 / (1.f + __expf(-g0)) * bf_lo(s[e]), g1 / (1.f + __expf(-g1)) * bf_hi(s[e])); }
;             *(v4u*)(obase + (size_t)r * DM + 8 * ch) = o; }
.Lro_w2:
	s_waitcnt vmcnt(22)
	v_and_b32_e32 v104, 0xffff0000, v87
	v_fma_f32 v16, -v93, v96, 1.0
	v_fmac_f32_e32 v96, v16, v96
	v_div_scale_f32 v16, vcc, v102, v98, v102
	v_mul_f32_e32 v94, v16, v96
	v_fma_f32 v97, -v93, v94, v16
	v_fmac_f32_e32 v94, v97, v96
	v_fma_f32 v16, -v93, v94, v16
	v_div_fmas_f32 v16, v16, v96, v94
	v_div_fixup_f32 v94, v16, v98, v102
	v_lshlrev_b32_e32 v96, 16, v101
	v_and_b32_e32 v97, 0xffff0000, v101
	v_pk_mul_f32 v[94:95], v[94:95], v[96:97]
	v_lshlrev_b32_e32 v98, 16, v86
	v_and_b32_e32 v86, 0xffff0000, v86
	v_cvt_pk_bf16_f32 v93, v94, v95
	v_mul_f32_e32 v94, 0xbfb8aa3b, v98
	v_mul_f32_e32 v95, 0xbfb8aa3b, v86
	v_exp_f32_e32 v94, v94
	v_exp_f32_e32 v95, v95
	v_lshlrev_b32_e32 v16, 13, v164
	v_lshl_add_u64 v[96:97], v[106:107], 0, v[16:17]
	global_store_dwordx4 v[96:97], v[90:93], off offset:2048
	v_or_b32_e32 v16, s4, v163
	s_nop 0
	v_pk_add_f32 v[90:91], v[94:95], 1.0 op_sel_hi:[1,0]
	v_mad_u64_u32 v[92:93], s[8:9], v16, s47, v[108:109]
	v_div_scale_f32 v99, s[8:9], v91, v91, v86
	v_rcp_f32_e32 v100, v99
	ds_read_b128 v[94:97], v92 offset:34816
	v_fma_f32 v16, -v99, v100, 1.0
	v_fmac_f32_e32 v100, v16, v100
	v_div_scale_f32 v16, vcc, v86, v91, v86
	v_mul_f32_e32 v92, v16, v100
	v_fma_f32 v93, -v99, v92, v16
	v_fmac_f32_e32 v92, v93, v100
	v_div_scale_f32 v93, s[8:9], v90, v90, v98
	v_rcp_f32_e32 v101, v93
	v_fma_f32 v16, -v99, v92, v16
	v_div_fmas_f32 v16, v16, v100, v92
	v_div_fixup_f32 v99, v16, v91, v86
	v_fma_f32 v16, -v93, v101, 1.0
	v_fmac_f32_e32 v101, v16, v101
	v_div_scale_f32 v16, vcc, v98, v90, v98
	v_mul_f32_e32 v86, v16, v101
	v_fma_f32 v91, -v93, v86, v16
	v_fmac_f32_e32 v86, v91, v101
	v_fma_f32 v16, -v93, v86, v16
	v_div_fmas_f32 v16, v16, v101, v86
	v_div_fixup_f32 v98, v16, v90, v98
	v_lshlrev_b32_e32 v16, 16, v87
	v_mul_f32_e32 v86, 0xbfb8aa3b, v16
	v_mul_f32_e32 v87, 0xbfb8aa3b, v104
	v_exp_f32_e32 v86, v86
	v_exp_f32_e32 v87, v87
	v_or_b32_e32 v90, s4, v162
	v_mad_u64_u32 v[90:91], s[4:5], v90, s47, v[108:109]
	v_pk_add_f32 v[102:103], v[86:87], 1.0 op_sel_hi:[1,0]
	s_waitcnt lgkmcnt(0)
	v_lshlrev_b32_e32 v100, 16, v94
	v_div_scale_f32 v105, s[4:5], v103, v103, v104
	v_rcp_f32_e32 v108, v105
	v_and_b32_e32 v101, 0xffff0000, v94
	v_pk_mul_f32 v[86:87], v[98:99], v[100:101]
	ds_read_b128 v[90:93], v90 offset:34816
	v_cvt_pk_bf16_f32 v86, v86, v87
	v_fma_f32 v87, -v105, v108, 1.0
	v_fmac_f32_e32 v108, v87, v108
	v_div_scale_f32 v87, vcc, v104, v103, v104
	v_mul_f32_e32 v94, v87, v108
	v_fma_f32 v98, -v105, v94, v87
	v_fmac_f32_e32 v94, v98, v108
	v_div_scale_f32 v98, s[4:5], v102, v102, v16
	v_fma_f32 v87, -v105, v94, v87
	v_rcp_f32_e32 v105, v98
	v_div_fmas_f32 v87, v87, v108, v94
	v_div_fixup_f32 v99, v87, v103, v104
	v_lshlrev_b32_e32 v103, 16, v88
	v_fma_f32 v87, -v98, v105, 1.0
	v_fmac_f32_e32 v105, v87, v105
	v_div_scale_f32 v87, vcc, v16, v102, v16
	v_mul_f32_e32 v94, v87, v105
	v_fma_f32 v100, -v98, v94, v87
	v_fmac_f32_e32 v94, v100, v105
	v_fma_f32 v87, -v98, v94, v87
	v_and_b32_e32 v88, 0xffff0000, v88
	v_mul_f32_e32 v98, 0xbfb8aa3b, v103
	v_exp_f32_e32 v100, v98
	v_mul_f32_e32 v98, 0xbfb8aa3b, v88
	v_exp_f32_e32 v101, v98
	v_div_fmas_f32 v87, v87, v105, v94
	v_div_fixup_f32 v98, v87, v102, v16
	v_lshlrev_b32_e32 v94, 16, v95
	v_pk_add_f32 v[100:101], v[100:101], 1.0 op_sel_hi:[1,0]
	v_and_b32_e32 v95, 0xffff0000, v95
	v_div_scale_f32 v16, s[4:5], v101, v101, v88
	v_rcp_f32_e32 v102, v16
	v_pk_mul_f32 v[94:95], v[98:99], v[94:95]
	v_and_b32_e32 v104, 0xffff0000, v89
	v_cvt_pk_bf16_f32 v87, v94, v95
	v_fma_f32 v94, -v16, v102, 1.0
	v_fmac_f32_e32 v102, v94, v102
	v_div_scale_f32 v94, vcc, v88, v101, v88
	v_mul_f32_e32 v95, v94, v102
	v_fma_f32 v98, -v16, v95, v94
	v_fmac_f32_e32 v95, v98, v102
	v_fma_f32 v16, -v16, v95, v94
	v_div_scale_f32 v94, s[4:5], v100, v100, v103
	v_rcp_f32_e32 v98, v94
	v_div_fmas_f32 v16, v16, v102, v95
	v_div_fixup_f32 v95, v16, v101, v88
	v_lshlrev_b32_e32 v102, 16, v89
	v_fma_f32 v16, -v94, v98, 1.0
	v_fmac_f32_e32 v98, v16, v98
	v_div_scale_f32 v16, vcc, v103, v100, v103
	v_mul_f32_e32 v99, v16, v98
	v_fma_f32 v88, -v94, v99, v16
	v_fmac_f32_e32 v99, v88, v98
	v_mul_f32_e32 v88, 0xbfb8aa3b, v102
	v_mul_f32_e32 v89, 0xbfb8aa3b, v104
	v_exp_f32_e32 v88, v88
	v_exp_f32_e32 v89, v89
	v_fma_f32 v16, -v94, v99, v16
	v_div_fmas_f32 v16, v16, v98, v99
	v_div_fixup_f32 v94, v16, v100, v103
	v_pk_add_f32 v[100:101], v[88:89], 1.0 op_sel_hi:[1,0]
	v_lshlrev_b32_e32 v98, 16, v96
	v_div_scale_f32 v16, s[4:5], v101, v101, v104
	v_rcp_f32_e32 v103, v16
	v_and_b32_e32 v99, 0xffff0000, v96
	v_pk_mul_f32 v[88:89], v[94:95], v[98:99]
	s_nop 0
	v_cvt_pk_bf16_f32 v88, v88, v89
	v_fma_f32 v89, -v16, v103, 1.0
	v_fmac_f32_e32 v103, v89, v103
	v_div_scale_f32 v89, vcc, v104, v101, v104
	v_mul_f32_e32 v94, v89, v103
	v_fma_f32 v95, -v16, v94, v89
	v_fmac_f32_e32 v94, v95, v103
	v_fma_f32 v16, -v16, v94, v89
	v_div_scale_f32 v89, s[4:5], v100, v100, v102
	v_rcp_f32_e32 v96, v89
	v_div_fmas_f32 v16, v16, v103, v94
	v_div_fixup_f32 v95, v16, v101, v104
	v_fma_f32 v16, -v89, v96, 1.0
	v_fmac_f32_e32 v96, v16, v96
	v_div_scale_f32 v16, vcc, v102, v100, v102
	v_mul_f32_e32 v94, v16, v96
	v_fma_f32 v98, -v89, v94, v16
	v_fmac_f32_e32 v94, v98, v96
	v_fma_f32 v16, -v89, v94, v16
	v_div_fmas_f32 v16, v16, v96, v94
	v_div_fixup_f32 v94, v16, v100, v102
	s_cmp_eq_u64 s[6:7], 0
	s_cbranch_scc1 .Lro_w3
	s_waitcnt vmcnt(2)
; __device__ __forceinline__ unsigned cvt_pk_bf16(float lo, float hi) { const f32x2c_t v = {lo, hi}; return __builtin_bit_cast(unsigned, __builtin_convertvector(v, bf16x2c_t)); }
; #define LAS __attribute__((address_space(3)))
; #define LDS_WAIT() asm volatile("s_waitcnt lgkmcnt(0)" ::: "memory")
; __device__ __forceinline__ float bf_lo(unsigned w) { return __uint_as_float(w << 16); }
; __device__ __forceinline__ float bf_hi(unsigned w) { return __uint_as_float(w & 0xffff0000u); }
; __device__ __forceinline__ void retout_loop(ldsp lds, const bf16* proj, const bf16* st, bf16* mix, const float* ldr, int u0, int ustep, int nunits, int tid0) {
;     ...
;         LDS_WAIT();
;         bf16* obase = mix + (row0 + 16 * w) * DM + MIX_R + h * HDIM;
; #pragma unroll
;         for (int k = 0; k < 4; ++k) { const int q = lane + 64 * k, r = q >> 4, ch = q & 15;
;             const v4u s = *(const LAS v4u*)(TK + offb(16 * w + r, ch)), gw = gr[k];
;             v4u o;
; #pragma unroll
;             for (int e = 0; e < 4; ++e) { const float g0 = bf_lo(gw[e]), g1 = bf_hi(gw[e]);
;                 o[e] = cvt_pk_bf16(g0 / (1.f + __expf(-g0)) * bf_lo(s[e]), g1 / (1.f + __expf(-g1)) * bf_hi(s[e])); }
;             *(v4u*)(obase + (size_t)r * DM + 8 * ch) = o; }
;         unit = unext;
.Lro_w3:
	s_waitcnt vmcnt(22)
	v_lshlrev_b32_e32 v100, 16, v82
	v_and_b32_e32 v82, 0xffff0000, v82
	v_mul_f32_e32 v16, 0xbfb8aa3b, v100
	v_exp_f32_e32 v98, v16
	v_mul_f32_e32 v16, 0xbfb8aa3b, v82
	v_exp_f32_e32 v99, v16
	v_lshlrev_b32_e32 v96, 16, v97
	v_and_b32_e32 v97, 0xffff0000, v97
	v_pk_mul_f32 v[94:95], v[94:95], v[96:97]
	v_lshlrev_b32_e32 v16, 13, v163
	v_cvt_pk_bf16_f32 v89, v94, v95
	v_pk_add_f32 v[94:95], v[98:99], 1.0 op_sel_hi:[1,0]
	v_lshl_add_u64 v[96:97], v[106:107], 0, v[16:17]
	v_div_scale_f32 v98, s[4:5], v95, v95, v82
	v_rcp_f32_e32 v99, v98
	global_store_dwordx4 v[96:97], v[86:89], off offset:2048
	v_lshlrev_b32_e32 v96, 16, v83
	v_and_b32_e32 v97, 0xffff0000, v83
	v_fma_f32 v16, -v98, v99, 1.0
	v_fmac_f32_e32 v99, v16, v99
	v_div_scale_f32 v16, vcc, v82, v95, v82
	v_mul_f32_e32 v86, v16, v99
	v_div_scale_f32 v88, s[4:5], v94, v94, v100
	v_fma_f32 v87, -v98, v86, v16
	v_rcp_f32_e32 v89, v88
	v_fmac_f32_e32 v86, v87, v99
	v_fma_f32 v16, -v98, v86, v16
	v_div_fmas_f32 v16, v16, v99, v86
	v_div_fixup_f32 v87, v16, v95, v82
	v_fma_f32 v16, -v88, v89, 1.0
	v_fmac_f32_e32 v89, v16, v89
	v_div_scale_f32 v16, vcc, v100, v94, v100
	v_mul_f32_e32 v86, v16, v89
	v_fma_f32 v82, -v88, v86, v16
	v_fmac_f32_e32 v86, v82, v89
	v_mul_f32_e32 v82, 0xbfb8aa3b, v96
	v_mul_f32_e32 v83, 0xbfb8aa3b, v97
	v_exp_f32_e32 v82, v82
	v_exp_f32_e32 v83, v83
	v_fma_f32 v16, -v88, v86, v16
	v_div_fmas_f32 v16, v16, v89, v86
	v_div_fixup_f32 v86, v16, v94, v100
	v_pk_add_f32 v[94:95], v[82:83], 1.0 op_sel_hi:[1,0]
	s_waitcnt lgkmcnt(0)
	v_lshlrev_b32_e32 v88, 16, v90
	v_div_scale_f32 v16, s[4:5], v95, v95, v97
	v_rcp_f32_e32 v98, v16
	v_and_b32_e32 v89, 0xffff0000, v90
	v_pk_mul_f32 v[82:83], v[86:87], v[88:89]
	s_nop 0
	v_cvt_pk_bf16_f32 v82, v82, v83
	v_fma_f32 v83, -v16, v98, 1.0
	v_fmac_f32_e32 v98, v83, v98
	v_div_scale_f32 v83, vcc, v97, v95, v97
	v_mul_f32_e32 v86, v83, v98
	v_fma_f32 v87, -v16, v86, v83
	v_fmac_f32_e32 v86, v87, v98
	v_fma_f32 v16, -v16, v86, v83
	v_div_scale_f32 v83, s[4:5], v94, v94, v96
	v_rcp_f32_e32 v90, v83
	v_div_fmas_f32 v16, v16, v98, v86
	v_div_fixup_f32 v87, v16, v95, v97
	v_lshlrev_b32_e32 v95, 16, v84
	v_fma_f32 v16, -v83, v90, 1.0
	v_fmac_f32_e32 v90, v16, v90
	v_div_scale_f32 v16, vcc, v96, v94, v96
	v_mul_f32_e32 v86, v16, v90
	v_fma_f32 v88, -v83, v86, v16
	v_fmac_f32_e32 v86, v88, v90
	v_fma_f32 v16, -v83, v86, v16
	v_and_b32_e32 v84, 0xffff0000, v84
	v_mul_f32_e32 v83, 0xbfb8aa3b, v95
	v_exp_f32_e32 v88, v83
	v_mul_f32_e32 v83, 0xbfb8aa3b, v84
	v_exp_f32_e32 v89, v83
	v_div_fmas_f32 v16, v16, v90, v86
	v_div_fixup_f32 v86, v16, v94, v96
	v_lshlrev_b32_e32 v90, 16, v91
	v_pk_add_f32 v[88:89], v[88:89], 1.0 op_sel_hi:[1,0]
	v_and_b32_e32 v91, 0xffff0000, v91
	v_div_scale_f32 v16, s[4:5], v89, v89, v84
	v_rcp_f32_e32 v94, v16
	v_pk_mul_f32 v[86:87], v[86:87], v[90:91]
	v_and_b32_e32 v96, 0xffff0000, v85
	v_cvt_pk_bf16_f32 v83, v86, v87
	v_fma_f32 v86, -v16, v94, 1.0
	v_fmac_f32_e32 v94, v86, v94
	v_div_scale_f32 v86, vcc, v84, v89, v84
	v_mul_f32_e32 v87, v86, v94
	v_fma_f32 v90, -v16, v87, v86
	v_fmac_f32_e32 v87, v90, v94
	v_fma_f32 v16, -v16, v87, v86
	v_div_scale_f32 v86, s[4:5], v88, v88, v95
	v_rcp_f32_e32 v90, v86
	v_div_fmas_f32 v16, v16, v94, v87
	v_div_fixup_f32 v87, v16, v89, v84
	v_lshlrev_b32_e32 v94, 16, v85
	v_fma_f32 v16, -v86, v90, 1.0
	v_fmac_f32_e32 v90, v16, v90
	v_div_scale_f32 v16, vcc, v95, v88, v95
	v_mul_f32_e32 v89, v16, v90
	v_fma_f32 v84, -v86, v89, v16
	v_fmac_f32_e32 v89, v84, v90
	v_mul_f32_e32 v84, 0xbfb8aa3b, v94
	v_mul_f32_e32 v85, 0xbfb8aa3b, v96
	v_exp_f32_e32 v84, v84
	v_exp_f32_e32 v85, v85
	v_fma_f32 v16, -v86, v89, v16
	v_div_fmas_f32 v16, v16, v90, v89
	v_div_fixup_f32 v86, v16, v88, v95
	v_pk_add_f32 v[90:91], v[84:85], 1.0 op_sel_hi:[1,0]
	v_lshlrev_b32_e32 v88, 16, v92
	v_div_scale_f32 v16, s[4:5], v91, v91, v96
	v_rcp_f32_e32 v95, v16
	v_and_b32_e32 v89, 0xffff0000, v92
	v_pk_mul_f32 v[84:85], v[86:87], v[88:89]
	s_nop 0
	v_cvt_pk_bf16_f32 v84, v84, v85
	v_fma_f32 v85, -v16, v95, 1.0
	v_fmac_f32_e32 v95, v85, v95
	v_div_scale_f32 v85, vcc, v96, v91, v96
	v_mul_f32_e32 v86, v85, v95
	v_fma_f32 v87, -v16, v86, v85
	v_fmac_f32_e32 v86, v87, v95
	v_fma_f32 v16, -v16, v86, v85
	v_div_scale_f32 v85, s[4:5], v90, v90, v94
	v_rcp_f32_e32 v88, v85
	v_div_fmas_f32 v16, v16, v95, v86
	v_div_fixup_f32 v87, v16, v91, v96
	v_readlane_b32 s4, v254, 46
	v_fma_f32 v16, -v85, v88, 1.0
	v_fmac_f32_e32 v88, v16, v88
	v_div_scale_f32 v16, vcc, v94, v90, v94
	v_mul_f32_e32 v86, v16, v88
	v_fma_f32 v89, -v85, v86, v16
	v_fmac_f32_e32 v86, v89, v88
	v_fma_f32 v16, -v85, v86, v16
	v_div_fmas_f32 v16, v16, v88, v86
	v_div_fixup_f32 v86, v16, v90, v94
	v_lshlrev_b32_e32 v88, 16, v93
	v_and_b32_e32 v89, 0xffff0000, v93
	v_pk_mul_f32 v[86:87], v[86:87], v[88:89]
	v_lshlrev_b32_e32 v16, 13, v162
	v_cvt_pk_bf16_f32 v85, v86, v87
	v_lshl_add_u64 v[86:87], v[106:107], 0, v[16:17]
	s_andn2_b64 vcc, exec, s[6:7]
	s_add_i32 s0, s0, s4
	global_store_dwordx4 v[86:87], v[82:85], off offset:2048
	s_cbranch_vccz .LBB0_464
; __device__ __forceinline__ void retout_loop(ldsp lds, const bf16* proj, const bf16* st, bf16* mix, const float* ldr, int u0, int ustep, int nunits, int tid0) {
;     ...
;     while (unit < nunits) {
;         asm volatile("" : "+v"(tid));
;         const int lane = tid & 63, w = __builtin_amdgcn_readfirstlane(tid >> 6), fr = lane & 15, fq = lane >> 4, i = 16 * w + fr;
;         const int h = unit & 7, n = (unit >> 3) & 31, b = unit >> 8;
;         const size_t row0 = (size_t)b * SEQ + (size_t)n * CHUNK;
;         const float l2f = -__expf(ldr[h]) * LOG2E, l2b = -__expf(ldr[NRH + h]) * LOG2E;
;         __syncthreads();
;         tile_put(TQ, R.q, tid); tile_put(TK, R.k, tid); tile_put(TV, R.v, tid); tile_put_frag(TS, R.sf, tid);
;         __syncthreads();
;         f32x4 P[8]; zero8(P);
;         mm128<false, false>(P, TQ, TK, w, lane);
.LBB0_462:
	s_and_b32 s5, s1, 7
	s_lshl_b32 s10, s5, 2
	s_add_i32 s11, s10, 32
	s_load_dword s10, s[14:15], s10
	s_load_dword s11, s[14:15], s11
	v_add_u32_e32 v85, 0x200, v170
	v_add_u32_e32 v87, 0x400, v170
	v_add_u32_e32 v89, 0x600, v170
	v_ashrrev_i32_e32 v162, 4, v170
	v_ashrrev_i32_e32 v164, 4, v85
	v_ashrrev_i32_e32 v166, 4, v87
	v_ashrrev_i32_e32 v168, 4, v89
	v_mul_lo_u32 v83, v162, s47
	v_mul_lo_u32 v85, v164, s47
	v_mul_lo_u32 v87, v166, s47
	v_mul_lo_u32 v89, v168, s47
	s_barrier
	v_and_b32_e32 v173, 15, v170
	s_mov_b32 s12, 0xffffff0
	v_readfirstlane_b32 s4, v170
	s_ashr_i32 s9, s4, 6
	v_and_b32_e32 v110, 48, v170
	s_lshl_b32 s4, s9, 4
	s_ashr_i32 s6, s1, 8
	s_mulk_i32 s9, 0x1100
	v_or_b32_e32 v174, s4, v173
	s_ashr_i32 s7, s6, 31
	s_and_b32 s8, s0, 0xf80
	s_waitcnt lgkmcnt(0)
	v_mov_b32_e32 v82, s10
	v_mul_f32_e32 v82, 0x3fb8aa3b, v82
	v_exp_f32_e32 v82, v82
	v_mov_b32_e32 v16, s11
	v_mul_f32_e32 v16, 0x3fb8aa3b, v16
	v_exp_f32_e32 v16, v16
	v_mul_f32_e32 v175, 0xbfb8aa3b, v82
	v_mul_f32_e32 v177, 0xbfb8aa3b, v16
	v_lshlrev_b32_e32 v16, 4, v170
	v_and_b32_e32 v16, 0xf0, v16
	v_add_u32_e32 v82, 0, v16
	v_add_u32_e32 v84, v82, v83
	v_add_u32_e32 v86, v82, v85
	v_add_u32_e32 v88, v82, v87
	v_add_u32_e32 v82, v82, v89
	v_add_u32_e32 v16, s33, v16
	s_waitcnt vmcnt(4)
	ds_write_b128 v84, v[0:3]
	ds_write_b128 v86, v[4:7]
	ds_write_b128 v88, v[8:11]
	ds_write_b128 v82, v[12:15]
	ds_write_b128 v84, v[18:21] offset:34816
	ds_write_b128 v86, v[22:25] offset:34816
	ds_write_b128 v88, v[26:29] offset:34816
	ds_write_b128 v82, v[30:33] offset:34816
	v_add_u32_e32 v82, v16, v83
	ds_write_b128 v82, v[34:37]
	v_add_u32_e32 v82, v16, v85
	ds_write_b128 v82, v[38:41]
	v_add_u32_e32 v82, v16, v87
	v_add_u32_e32 v16, v16, v89
	ds_write_b128 v82, v[42:45]
	ds_write_b128 v16, v[46:49]
	v_and_b32_e32 v16, 0xf0, v170
	v_add_u32_e32 v16, s96, v16
	v_and_or_b32 v82, v162, s12, v173
	v_mad_u64_u32 v[130:131], s[10:11], v82, s47, v[16:17]
	v_and_or_b32 v82, v164, s12, v173
	v_mad_u64_u32 v[132:133], s[10:11], v82, s47, v[16:17]
	v_and_or_b32 v82, v166, s12, v173
	v_mad_u64_u32 v[134:135], s[10:11], v82, s47, v[16:17]
	v_and_or_b32 v82, v168, s12, v173
	v_mad_u64_u32 v[136:137], s[10:11], v82, s47, v[16:17]
	v_mul_u32_u24_e32 v16, 0x110, v173
	v_add3_u32 v82, 0, v16, v110
	v_add_u32_e32 v176, s9, v82
	ds_write_b128 v130, v[50:53]
	ds_write_b128 v132, v[54:57]
	ds_write_b128 v134, v[58:61]
	ds_write_b128 v136, v[62:65]
	s_waitcnt lgkmcnt(0)
	s_barrier
	s_setprio 1
	ds_read_b128 v[150:153], v176
	ds_read_b128 v[154:157], v82 offset:34816
	ds_read_b128 v[158:161], v82 offset:39168
	ds_read_b128 v[178:181], v82 offset:43520
	ds_read_b128 v[182:185], v82 offset:47872
	ds_read_b128 v[186:189], v82 offset:52224
	ds_read_b128 v[190:193], v82 offset:56576
	ds_read_b128 v[194:197], v82 offset:60928
	ds_read_b128 v[198:201], v82 offset:65280
	ds_read_b128 v[202:205], v176 offset:64
	ds_read_b128 v[206:209], v82 offset:34880
	ds_read_b128 v[212:215], v82 offset:39232
	s_waitcnt lgkmcnt(10)
	v_mfma_f32_16x16x32_bf16 v[88:91], v[154:157], v[150:153], 0
	ds_read_b128 v[154:157], v82 offset:43584
	s_waitcnt lgkmcnt(10)
	v_mfma_f32_16x16x32_bf16 v[92:95], v[158:161], v[150:153], 0
	ds_read_b128 v[158:161], v82 offset:47936
	s_waitcnt lgkmcnt(10)
	v_mfma_f32_16x16x32_bf16 v[96:99], v[178:181], v[150:153], 0
	ds_read_b128 v[178:181], v82 offset:52288
	s_waitcnt lgkmcnt(10)
	v_mfma_f32_16x16x32_bf16 v[100:103], v[182:185], v[150:153], 0
	ds_read_b128 v[182:185], v82 offset:56640
	s_waitcnt lgkmcnt(10)
	v_mfma_f32_16x16x32_bf16 v[104:107], v[186:189], v[150:153], 0
	ds_read_b128 v[186:189], v82 offset:60992
	s_waitcnt lgkmcnt(10)
	v_mfma_f32_16x16x32_bf16 v[112:115], v[190:193], v[150:153], 0
	ds_read_b128 v[190:193], v82 offset:65344
	s_waitcnt lgkmcnt(10)
	v_mfma_f32_16x16x32_bf16 v[116:119], v[194:197], v[150:153], 0
	ds_read_b128 v[194:197], v176 offset:128
	s_waitcnt lgkmcnt(10)
	v_mfma_f32_16x16x32_bf16 v[84:87], v[198:201], v[150:153], 0
	ds_read_b128 v[198:201], v82 offset:34944
	ds_read_b128 v[150:153], v82 offset:39296
	s_waitcnt lgkmcnt(10)
	v_mfma_f32_16x16x32_bf16 v[88:91], v[206:209], v[202:205], v[88:91]
	ds_read_b128 v[206:209], v82 offset:43648
	s_waitcnt lgkmcnt(10)
	v_mfma_f32_16x16x32_bf16 v[92:95], v[212:215], v[202:205], v[92:95]
	ds_read_b128 v[212:215], v82 offset:48000
	s_waitcnt lgkmcnt(10)
	v_mfma_f32_16x16x32_bf16 v[96:99], v[154:157], v[202:205], v[96:99]
	ds_read_b128 v[154:157], v82 offset:52352
	s_waitcnt lgkmcnt(10)
	v_mfma_f32_16x16x32_bf16 v[100:103], v[158:161], v[202:205], v[100:103]
	ds_read_b128 v[158:161], v82 offset:56704
	s_waitcnt lgkmcnt(10)
	v_mfma_f32_16x16x32_bf16 v[104:107], v[178:181], v[202:205], v[104:107]
	ds_read_b128 v[178:181], v82 offset:61056
	s_waitcnt lgkmcnt(10)
	v_mfma_f32_16x16x32_bf16 v[112:115], v[182:185], v[202:205], v[112:115]
	ds_read_b128 v[182:185], v82 offset:65408
	s_waitcnt lgkmcnt(10)
	v_mfma_f32_16x16x32_bf16 v[116:119], v[186:189], v[202:205], v[116:119]
	ds_read_b128 v[186:189], v176 offset:192
	s_waitcnt lgkmcnt(10)
	v_mfma_f32_16x16x32_bf16 v[84:87], v[190:193], v[202:205], v[84:87]
	ds_read_b128 v[190:193], v82 offset:35008
	ds_read_b128 v[202:205], v82 offset:39360
	s_waitcnt lgkmcnt(10)
	v_mfma_f32_16x16x32_bf16 v[88:91], v[198:201], v[194:197], v[88:91]
	ds_read_b128 v[198:201], v82 offset:43712
	s_waitcnt lgkmcnt(10)
	v_mfma_f32_16x16x32_bf16 v[92:95], v[150:153], v[194:197], v[92:95]
	ds_read_b128 v[150:153], v82 offset:48064
	s_waitcnt lgkmcnt(10)
	v_mfma_f32_16x16x32_bf16 v[96:99], v[206:209], v[194:197], v[96:99]
	ds_read_b128 v[206:209], v82 offset:52416
	s_waitcnt lgkmcnt(10)
; __device__ __forceinline__ void retout_loop(ldsp lds, const bf16* proj, const bf16* st, bf16* mix, const float* ldr, int u0, int ustep, int nunits, int tid0) {
;     ...
;         mm128<false, false>(P, TQ, TK, w, lane);
; #pragma unroll
;         for (int c = 0; c < 8; ++c)
; #pragma unroll
;             for (int j = 0; j < 4; ++j) { const int dl = i - (16 * c + 4 * fq + j);
;                 P[c][j] *= __builtin_amdgcn_exp2f(dl >= 0 ? l2f * (float)dl : l2b * (float)(-dl)); }
	v_mfma_f32_16x16x32_bf16 v[124:127], v[212:215], v[194:197], v[100:103]
	ds_read_b128 v[212:215], v82 offset:56768
	s_waitcnt lgkmcnt(10)
	v_mfma_f32_16x16x32_bf16 v[138:141], v[154:157], v[194:197], v[104:107]
	ds_read_b128 v[154:157], v82 offset:61120
	s_waitcnt lgkmcnt(10)
	v_mfma_f32_16x16x32_bf16 v[112:115], v[158:161], v[194:197], v[112:115]
	ds_read_b128 v[158:161], v82 offset:65472
	s_waitcnt lgkmcnt(10)
	v_mfma_f32_16x16x32_bf16 v[116:119], v[178:181], v[194:197], v[116:119]
	s_waitcnt lgkmcnt(9)
	v_mfma_f32_16x16x32_bf16 v[120:123], v[182:185], v[194:197], v[84:87]
	s_waitcnt lgkmcnt(7)
	v_mfma_f32_16x16x32_bf16 v[146:149], v[190:193], v[186:189], v[88:91]
	s_waitcnt lgkmcnt(6)
	v_mfma_f32_16x16x32_bf16 v[106:109], v[202:205], v[186:189], v[92:95]
	s_waitcnt lgkmcnt(5)
	v_mfma_f32_16x16x32_bf16 v[102:105], v[198:201], v[186:189], v[96:99]
	s_waitcnt lgkmcnt(4)
	v_mfma_f32_16x16x32_bf16 v[98:101], v[150:153], v[186:189], v[124:127]
	s_waitcnt lgkmcnt(3)
	v_mfma_f32_16x16x32_bf16 v[94:97], v[206:209], v[186:189], v[138:141]
	s_waitcnt lgkmcnt(2)
	v_mfma_f32_16x16x32_bf16 v[90:93], v[212:215], v[186:189], v[112:115]
	s_waitcnt lgkmcnt(1)
	v_mfma_f32_16x16x32_bf16 v[86:89], v[154:157], v[186:189], v[116:119]
	s_waitcnt lgkmcnt(0)
	v_mfma_f32_16x16x32_bf16 v[82:85], v[158:161], v[186:189], v[120:123]
	s_nop 7
	s_setprio 0
	v_lshrrev_b32_e32 v111, 2, v170
	v_and_b32_e32 v111, 12, v111
	v_sub_u32_e32 v112, v174, v111
	v_sub_u32_e32 v113, 0, v112
	v_max_i32_e32 v113, v112, v113
	v_cvt_f32_u32_e32 v113, v113
	v_cmp_gt_i32_e32 vcc, 0, v112
	s_lshl_b64 s[6:7], s[6:7], 12
	s_or_b32 s6, s6, s8
	v_cndmask_b32_e32 v112, v175, v177, vcc
	v_mul_f32_e32 v112, v112, v113
	v_xad_u32 v113, v111, -1, v174
	v_sub_u32_e32 v114, 0, v113
	v_max_i32_e32 v114, v113, v114
	v_cvt_f32_u32_e32 v114, v114
	v_cmp_gt_i32_e32 vcc, 0, v113
	v_exp_f32_e32 v112, v112
	v_add3_u32 v158, s96, v16, v110
	v_cndmask_b32_e32 v113, v175, v177, vcc
	v_mul_f32_e32 v113, v113, v114
	v_exp_f32_e32 v113, v113
	s_nop 0
	v_pk_mul_f32 v[138:139], v[112:113], v[146:147]
	v_or_b32_e32 v112, 2, v111
	v_sub_u32_e32 v112, v174, v112
	v_sub_u32_e32 v113, 0, v112
	v_max_i32_e32 v113, v112, v113
	v_cvt_f32_u32_e32 v113, v113
	v_cmp_gt_i32_e32 vcc, 0, v112
	s_nop 1
	v_cndmask_b32_e32 v112, v175, v177, vcc
	v_mul_f32_e32 v112, v112, v113
	v_or_b32_e32 v113, 3, v111
	v_sub_u32_e32 v113, v174, v113
	v_sub_u32_e32 v114, 0, v113
	v_max_i32_e32 v114, v113, v114
	v_cvt_f32_u32_e32 v114, v114
	v_cmp_gt_i32_e32 vcc, 0, v113
	v_exp_f32_e32 v112, v112
	s_nop 0
	v_cndmask_b32_e32 v113, v175, v177, vcc
	v_mul_f32_e32 v113, v113, v114
	v_exp_f32_e32 v113, v113
	s_nop 0
	v_pk_mul_f32 v[140:141], v[112:113], v[148:149]
	v_or_b32_e32 v112, 16, v111
	v_sub_u32_e32 v112, v174, v112
	v_sub_u32_e32 v113, 0, v112
	v_max_i32_e32 v113, v112, v113
	v_cvt_f32_u32_e32 v113, v113
	v_cmp_gt_i32_e32 vcc, 0, v112
	s_nop 1
	v_cndmask_b32_e32 v112, v175, v177, vcc
	v_mul_f32_e32 v112, v112, v113
	v_or_b32_e32 v113, 17, v111
	v_sub_u32_e32 v113, v174, v113
	v_sub_u32_e32 v114, 0, v113
	v_max_i32_e32 v114, v113, v114
	v_cvt_f32_u32_e32 v114, v114
	v_cmp_gt_i32_e32 vcc, 0, v113
	v_exp_f32_e32 v112, v112
	s_nop 0
	v_cndmask_b32_e32 v113, v175, v177, vcc
	v_mul_f32_e32 v113, v113, v114
	v_exp_f32_e32 v113, v113
	s_nop 0
	v_pk_mul_f32 v[142:143], v[112:113], v[106:107]
	v_or_b32_e32 v106, 18, v111
	v_sub_u32_e32 v106, v174, v106
	v_sub_u32_e32 v107, 0, v106
	v_max_i32_e32 v107, v106, v107
	v_cvt_f32_u32_e32 v107, v107
	v_cmp_gt_i32_e32 vcc, 0, v106
	s_nop 1
	v_cndmask_b32_e32 v106, v175, v177, vcc
	v_mul_f32_e32 v106, v106, v107
	v_or_b32_e32 v107, 19, v111
	v_sub_u32_e32 v107, v174, v107
	v_sub_u32_e32 v112, 0, v107
	v_max_i32_e32 v112, v107, v112
	v_cvt_f32_u32_e32 v112, v112
	v_cmp_gt_i32_e32 vcc, 0, v107
	v_exp_f32_e32 v106, v106
	s_nop 0
	v_cndmask_b32_e32 v107, v175, v177, vcc
	v_mul_f32_e32 v107, v107, v112
	v_exp_f32_e32 v107, v107
	s_nop 0
	v_pk_mul_f32 v[144:145], v[106:107], v[108:109]
	v_or_b32_e32 v106, 32, v111
	v_sub_u32_e32 v106, v174, v106
	v_sub_u32_e32 v107, 0, v106
	v_max_i32_e32 v107, v106, v107
	v_cvt_f32_u32_e32 v107, v107
	v_cmp_gt_i32_e32 vcc, 0, v106
	s_nop 1
	v_cndmask_b32_e32 v106, v175, v177, vcc
	v_mul_f32_e32 v106, v106, v107
	v_or_b32_e32 v107, 33, v111
	v_sub_u32_e32 v107, v174, v107
	v_sub_u32_e32 v108, 0, v107
	v_max_i32_e32 v108, v107, v108
	v_cvt_f32_u32_e32 v108, v108
	v_cmp_gt_i32_e32 vcc, 0, v107
	v_exp_f32_e32 v106, v106
	s_nop 0
	v_cndmask_b32_e32 v107, v175, v177, vcc
	v_mul_f32_e32 v107, v107, v108
	v_exp_f32_e32 v107, v107
	s_nop 0
	v_pk_mul_f32 v[146:147], v[106:107], v[102:103]
	v_or_b32_e32 v102, 34, v111
	v_sub_u32_e32 v102, v174, v102
	v_sub_u32_e32 v103, 0, v102
	v_max_i32_e32 v103, v102, v103
	v_cvt_f32_u32_e32 v103, v103
	v_cmp_gt_i32_e32 vcc, 0, v102
	s_nop 1
	v_cndmask_b32_e32 v102, v175, v177, vcc
	v_mul_f32_e32 v102, v102, v103
	v_or_b32_e32 v103, 35, v111
	v_sub_u32_e32 v103, v174, v103
	v_sub_u32_e32 v106, 0, v103
	v_max_i32_e32 v106, v103, v106
	v_cvt_f32_u32_e32 v106, v106
	v_cmp_gt_i32_e32 vcc, 0, v103
	v_exp_f32_e32 v102, v102
	s_nop 0
	v_cndmask_b32_e32 v103, v175, v177, vcc
	v_mul_f32_e32 v103, v103, v106
	v_exp_f32_e32 v103, v103
	s_nop 0
	v_pk_mul_f32 v[148:149], v[102:103], v[104:105]
	v_or_b32_e32 v102, 48, v111
	v_sub_u32_e32 v102, v174, v102
	v_sub_u32_e32 v103, 0, v102
	v_max_i32_e32 v103, v102, v103
	v_cvt_f32_u32_e32 v103, v103
	v_cmp_gt_i32_e32 vcc, 0, v102
	s_nop 1
	v_cndmask_b32_e32 v102, v175, v177, vcc
	v_mul_f32_e32 v102, v102, v103
	v_or_b32_e32 v103, 49, v111
	v_sub_u32_e32 v103, v174, v103
	v_sub_u32_e32 v104, 0, v103
	v_max_i32_e32 v104, v103, v104
; __device__ __forceinline__ void retout_loop(ldsp lds, const bf16* proj, const bf16* st, bf16* mix, const float* ldr, int u0, int ustep, int nunits, int tid0) {
;     ...
; #pragma unroll
;         for (int c = 0; c < 8; ++c)
; #pragma unroll
;             for (int j = 0; j < 4; ++j) { const int dl = i - (16 * c + 4 * fq + j);
;                 P[c][j] *= __builtin_amdgcn_exp2f(dl >= 0 ? l2f * (float)dl : l2b * (float)(-dl)); }
;         f32x4 accF[8]; zero8(accF);
;         mm128<false, false>(accF, TQ, TS, w, lane);
	v_cvt_f32_u32_e32 v104, v104
	v_cmp_gt_i32_e32 vcc, 0, v103
	v_exp_f32_e32 v102, v102
	s_nop 0
	v_cndmask_b32_e32 v103, v175, v177, vcc
	v_mul_f32_e32 v103, v103, v104
	v_exp_f32_e32 v103, v103
	s_nop 0
	v_pk_mul_f32 v[150:151], v[102:103], v[98:99]
	v_or_b32_e32 v98, 50, v111
	v_sub_u32_e32 v98, v174, v98
	v_sub_u32_e32 v99, 0, v98
	v_max_i32_e32 v99, v98, v99
	v_cvt_f32_u32_e32 v99, v99
	v_cmp_gt_i32_e32 vcc, 0, v98
	s_nop 1
	v_cndmask_b32_e32 v98, v175, v177, vcc
	v_mul_f32_e32 v98, v98, v99
	v_or_b32_e32 v99, 51, v111
	v_sub_u32_e32 v99, v174, v99
	v_sub_u32_e32 v102, 0, v99
	v_max_i32_e32 v102, v99, v102
	v_cvt_f32_u32_e32 v102, v102
	v_cmp_gt_i32_e32 vcc, 0, v99
	v_exp_f32_e32 v98, v98
	s_nop 0
	v_cndmask_b32_e32 v99, v175, v177, vcc
	v_mul_f32_e32 v99, v99, v102
	v_exp_f32_e32 v99, v99
	s_nop 0
	v_pk_mul_f32 v[152:153], v[98:99], v[100:101]
	v_or_b32_e32 v98, 64, v111
	v_sub_u32_e32 v98, v174, v98
	v_sub_u32_e32 v99, 0, v98
	v_max_i32_e32 v99, v98, v99
	v_cvt_f32_u32_e32 v99, v99
	v_cmp_gt_i32_e32 vcc, 0, v98
	s_nop 1
	v_cndmask_b32_e32 v98, v175, v177, vcc
	v_mul_f32_e32 v98, v98, v99
	v_or_b32_e32 v99, 0x41, v111
	v_sub_u32_e32 v99, v174, v99
	v_sub_u32_e32 v100, 0, v99
	v_max_i32_e32 v100, v99, v100
	v_cvt_f32_u32_e32 v100, v100
	v_cmp_gt_i32_e32 vcc, 0, v99
	v_exp_f32_e32 v98, v98
	s_nop 0
	v_cndmask_b32_e32 v99, v175, v177, vcc
	v_mul_f32_e32 v99, v99, v100
	v_exp_f32_e32 v99, v99
	s_nop 0
	v_pk_mul_f32 v[94:95], v[98:99], v[94:95]
	v_or_b32_e32 v98, 0x42, v111
	v_sub_u32_e32 v98, v174, v98
	v_sub_u32_e32 v99, 0, v98
	v_max_i32_e32 v99, v98, v99
	v_cvt_f32_u32_e32 v99, v99
	v_cmp_gt_i32_e32 vcc, 0, v98
	s_nop 1
	v_cndmask_b32_e32 v98, v175, v177, vcc
	v_mul_f32_e32 v98, v98, v99
	v_or_b32_e32 v99, 0x43, v111
	v_sub_u32_e32 v99, v174, v99
	v_sub_u32_e32 v100, 0, v99
	v_max_i32_e32 v100, v99, v100
	v_cvt_f32_u32_e32 v100, v100
	v_cmp_gt_i32_e32 vcc, 0, v99
	v_exp_f32_e32 v98, v98
	s_nop 0
	v_cndmask_b32_e32 v99, v175, v177, vcc
	v_mul_f32_e32 v99, v99, v100
	v_exp_f32_e32 v99, v99
	s_nop 0
	v_pk_mul_f32 v[96:97], v[98:99], v[96:97]
	v_or_b32_e32 v98, 0x50, v111
	v_sub_u32_e32 v98, v174, v98
	v_sub_u32_e32 v99, 0, v98
	v_max_i32_e32 v99, v98, v99
	v_cvt_f32_u32_e32 v99, v99
	v_cmp_gt_i32_e32 vcc, 0, v98
	s_nop 1
	v_cndmask_b32_e32 v98, v175, v177, vcc
	v_mul_f32_e32 v98, v98, v99
	v_or_b32_e32 v99, 0x51, v111
	v_sub_u32_e32 v99, v174, v99
	v_sub_u32_e32 v100, 0, v99
	v_max_i32_e32 v100, v99, v100
	v_cvt_f32_u32_e32 v100, v100
	v_cmp_gt_i32_e32 vcc, 0, v99
	v_exp_f32_e32 v98, v98
	s_nop 0
	v_cndmask_b32_e32 v99, v175, v177, vcc
	v_mul_f32_e32 v99, v99, v100
	v_exp_f32_e32 v99, v99
	s_nop 0
	v_pk_mul_f32 v[90:91], v[98:99], v[90:91]
	v_or_b32_e32 v98, 0x52, v111
	v_sub_u32_e32 v98, v174, v98
	v_sub_u32_e32 v99, 0, v98
	v_max_i32_e32 v99, v98, v99
	v_cvt_f32_u32_e32 v99, v99
	v_cmp_gt_i32_e32 vcc, 0, v98
	s_nop 1
	v_cndmask_b32_e32 v98, v175, v177, vcc
	v_mul_f32_e32 v98, v98, v99
	v_or_b32_e32 v99, 0x53, v111
	v_sub_u32_e32 v99, v174, v99
	v_sub_u32_e32 v100, 0, v99
	v_max_i32_e32 v100, v99, v100
	v_cvt_f32_u32_e32 v100, v100
	v_cmp_gt_i32_e32 vcc, 0, v99
	v_exp_f32_e32 v98, v98
	s_nop 0
	v_cndmask_b32_e32 v99, v175, v177, vcc
	v_mul_f32_e32 v99, v99, v100
	v_exp_f32_e32 v99, v99
	s_nop 0
	v_pk_mul_f32 v[92:93], v[98:99], v[92:93]
	v_or_b32_e32 v98, 0x60, v111
	v_sub_u32_e32 v98, v174, v98
	v_sub_u32_e32 v99, 0, v98
	v_max_i32_e32 v99, v98, v99
	v_cvt_f32_u32_e32 v99, v99
	v_cmp_gt_i32_e32 vcc, 0, v98
	s_nop 1
	v_cndmask_b32_e32 v98, v175, v177, vcc
	v_mul_f32_e32 v98, v98, v99
	v_or_b32_e32 v99, 0x61, v111
	v_sub_u32_e32 v99, v174, v99
	v_sub_u32_e32 v100, 0, v99
	v_max_i32_e32 v100, v99, v100
	v_cvt_f32_u32_e32 v100, v100
	v_cmp_gt_i32_e32 vcc, 0, v99
	v_exp_f32_e32 v98, v98
	s_nop 0
	v_cndmask_b32_e32 v99, v175, v177, vcc
	v_mul_f32_e32 v99, v99, v100
	v_exp_f32_e32 v99, v99
	s_nop 0
	v_pk_mul_f32 v[86:87], v[98:99], v[86:87]
	v_or_b32_e32 v98, 0x62, v111
	v_sub_u32_e32 v98, v174, v98
	v_sub_u32_e32 v99, 0, v98
	v_max_i32_e32 v99, v98, v99
	v_cvt_f32_u32_e32 v99, v99
	v_cmp_gt_i32_e32 vcc, 0, v98
	s_nop 1
	v_cndmask_b32_e32 v98, v175, v177, vcc
	v_mul_f32_e32 v98, v98, v99
	v_or_b32_e32 v99, 0x63, v111
	v_sub_u32_e32 v99, v174, v99
	v_sub_u32_e32 v100, 0, v99
	v_max_i32_e32 v100, v99, v100
	v_cvt_f32_u32_e32 v100, v100
	v_cmp_gt_i32_e32 vcc, 0, v99
	v_exp_f32_e32 v98, v98
	s_nop 0
	v_cndmask_b32_e32 v99, v175, v177, vcc
	v_mul_f32_e32 v99, v99, v100
	v_exp_f32_e32 v99, v99
	s_nop 0
	v_pk_mul_f32 v[88:89], v[98:99], v[88:89]
	v_or_b32_e32 v98, 0x70, v111
	v_sub_u32_e32 v98, v174, v98
	v_sub_u32_e32 v99, 0, v98
	v_max_i32_e32 v99, v98, v99
	v_cvt_f32_u32_e32 v99, v99
	v_cmp_gt_i32_e32 vcc, 0, v98
	s_nop 1
	v_cndmask_b32_e32 v98, v175, v177, vcc
	v_mul_f32_e32 v98, v98, v99
	v_or_b32_e32 v99, 0x71, v111
	v_sub_u32_e32 v99, v174, v99
	v_sub_u32_e32 v100, 0, v99
	v_max_i32_e32 v100, v99, v100
	v_cvt_f32_u32_e32 v100, v100
	v_cmp_gt_i32_e32 vcc, 0, v99
	v_exp_f32_e32 v98, v98
	s_nop 0
	v_cndmask_b32_e32 v99, v175, v177, vcc
	v_mul_f32_e32 v99, v99, v100
	v_exp_f32_e32 v99, v99
	s_nop 0
	v_pk_mul_f32 v[82:83], v[98:99], v[82:83]
	v_or_b32_e32 v98, 0x72, v111
	v_sub_u32_e32 v98, v174, v98
	v_sub_u32_e32 v99, 0, v98
	v_max_i32_e32 v99, v98, v99
	v_cvt_f32_u32_e32 v99, v99
	v_cmp_gt_i32_e32 vcc, 0, v98
	s_nop 1
	v_cndmask_b32_e32 v98, v175, v177, vcc
	v_mul_f32_e32 v98, v98, v99
	v_or_b32_e32 v99, 0x73, v111
	v_sub_u32_e32 v99, v174, v99
	v_sub_u32_e32 v100, 0, v99
	v_max_i32_e32 v100, v99, v100
	v_cvt_f32_u32_e32 v100, v100
	v_cmp_gt_i32_e32 vcc, 0, v99
	v_exp_f32_e32 v98, v98
	s_nop 0
	v_cndmask_b32_e32 v99, v175, v177, vcc
	v_mul_f32_e32 v99, v99, v100
	v_exp_f32_e32 v99, v99
	s_nop 0
	v_pk_mul_f32 v[84:85], v[98:99], v[84:85]
	s_setprio 1
	ds_read_b128 v[194:197], v176
	ds_read_b128 v[198:201], v158
	ds_read_b128 v[202:205], v158 offset:4352
	ds_read_b128 v[206:209], v158 offset:8704
	ds_read_b128 v[212:215], v158 offset:13056
	ds_read_b128 v[216:219], v158 offset:17408
	ds_read_b128 v[220:223], v158 offset:21760
	ds_read_b128 v[236:239], v158 offset:26112
	s_waitcnt lgkmcnt(6)
; __device__ __forceinline__ void retout_loop(ldsp lds, const bf16* proj, const bf16* st, bf16* mix, const float* ldr, int u0, int ustep, int nunits, int tid0) {
;     ...
;         mm128<false, false>(accF, TQ, TS, w, lane);
;         __syncthreads();
;         store_acc_tile(TK, P, w, lane);
	v_mfma_f32_16x16x32_bf16 v[102:105], v[198:201], v[194:197], 0
	ds_read_b128 v[198:201], v158 offset:30464
	s_waitcnt lgkmcnt(6)
	v_mfma_f32_16x16x32_bf16 v[106:109], v[202:205], v[194:197], 0
	ds_read_b128 v[202:205], v176 offset:64
	s_waitcnt lgkmcnt(6)
	v_mfma_f32_16x16x32_bf16 v[110:113], v[206:209], v[194:197], 0
	ds_read_b128 v[206:209], v158 offset:64
	s_waitcnt lgkmcnt(6)
	v_mfma_f32_16x16x32_bf16 v[114:117], v[212:215], v[194:197], 0
	ds_read_b128 v[212:215], v158 offset:4416
	s_waitcnt lgkmcnt(6)
	v_mfma_f32_16x16x32_bf16 v[118:121], v[216:219], v[194:197], 0
	ds_read_b128 v[216:219], v158 offset:8768
	s_waitcnt lgkmcnt(6)
	v_mfma_f32_16x16x32_bf16 v[122:125], v[220:223], v[194:197], 0
	ds_read_b128 v[220:223], v158 offset:13120
	s_waitcnt lgkmcnt(6)
	v_mfma_f32_16x16x32_bf16 v[126:129], v[236:239], v[194:197], 0
	ds_read_b128 v[236:239], v158 offset:17472
	s_waitcnt lgkmcnt(6)
	v_mfma_f32_16x16x32_bf16 v[98:101], v[198:201], v[194:197], 0
	ds_read_b128 v[198:201], v158 offset:21824
	ds_read_b128 v[194:197], v158 offset:26176
	s_waitcnt lgkmcnt(6)
	v_mfma_f32_16x16x32_bf16 v[102:105], v[206:209], v[202:205], v[102:105]
	ds_read_b128 v[206:209], v158 offset:30528
	s_waitcnt lgkmcnt(6)
	v_mfma_f32_16x16x32_bf16 v[106:109], v[212:215], v[202:205], v[106:109]
	ds_read_b128 v[212:215], v176 offset:128
	s_waitcnt lgkmcnt(6)
	v_mfma_f32_16x16x32_bf16 v[110:113], v[216:219], v[202:205], v[110:113]
	ds_read_b128 v[216:219], v158 offset:128
	s_waitcnt lgkmcnt(6)
	v_mfma_f32_16x16x32_bf16 v[114:117], v[220:223], v[202:205], v[114:117]
	ds_read_b128 v[220:223], v158 offset:4480
	s_waitcnt lgkmcnt(6)
	v_mfma_f32_16x16x32_bf16 v[118:121], v[236:239], v[202:205], v[118:121]
	ds_read_b128 v[236:239], v158 offset:8832
	s_waitcnt lgkmcnt(6)
	v_mfma_f32_16x16x32_bf16 v[122:125], v[198:201], v[202:205], v[122:125]
	ds_read_b128 v[198:201], v158 offset:13184
	s_waitcnt lgkmcnt(6)
	v_mfma_f32_16x16x32_bf16 v[126:129], v[194:197], v[202:205], v[126:129]
	ds_read_b128 v[194:197], v158 offset:17536
	s_waitcnt lgkmcnt(6)
	v_mfma_f32_16x16x32_bf16 v[98:101], v[206:209], v[202:205], v[98:101]
	ds_read_b128 v[206:209], v158 offset:21888
	ds_read_b128 v[202:205], v158 offset:26240
	s_waitcnt lgkmcnt(6)
	v_mfma_f32_16x16x32_bf16 v[102:105], v[216:219], v[212:215], v[102:105]
	ds_read_b128 v[216:219], v158 offset:30592
	s_waitcnt lgkmcnt(6)
	v_mfma_f32_16x16x32_bf16 v[106:109], v[220:223], v[212:215], v[106:109]
	ds_read_b128 v[220:223], v176 offset:192
	s_waitcnt lgkmcnt(6)
	v_mfma_f32_16x16x32_bf16 v[110:113], v[236:239], v[212:215], v[110:113]
	ds_read_b128 v[236:239], v158 offset:192
	s_waitcnt lgkmcnt(6)
	v_mfma_f32_16x16x32_bf16 v[178:181], v[198:201], v[212:215], v[114:117]
	ds_read_b128 v[198:201], v158 offset:4544
	s_waitcnt lgkmcnt(6)
	v_mfma_f32_16x16x32_bf16 v[182:185], v[194:197], v[212:215], v[118:121]
	ds_read_b128 v[194:197], v158 offset:8896
	s_waitcnt lgkmcnt(6)
	v_mfma_f32_16x16x32_bf16 v[186:189], v[206:209], v[212:215], v[122:125]
	ds_read_b128 v[206:209], v158 offset:13248
	s_waitcnt lgkmcnt(6)
	v_mfma_f32_16x16x32_bf16 v[126:129], v[202:205], v[212:215], v[126:129]
	ds_read_b128 v[202:205], v158 offset:17600
	s_waitcnt lgkmcnt(6)
	v_mfma_f32_16x16x32_bf16 v[154:157], v[216:219], v[212:215], v[98:101]
	ds_read_b128 v[216:219], v158 offset:21952
	ds_read_b128 v[212:215], v158 offset:26304
	s_waitcnt lgkmcnt(6)
	v_mfma_f32_16x16x32_bf16 v[114:117], v[236:239], v[220:223], v[102:105]
	ds_read_b128 v[236:239], v158 offset:30656
	s_waitcnt lgkmcnt(6)
	v_mfma_f32_16x16x32_bf16 v[122:125], v[198:201], v[220:223], v[106:109]
	s_waitcnt lgkmcnt(5)
	v_mfma_f32_16x16x32_bf16 v[118:121], v[194:197], v[220:223], v[110:113]
	s_waitcnt lgkmcnt(4)
	v_mfma_f32_16x16x32_bf16 v[110:113], v[206:209], v[220:223], v[178:181]
	s_waitcnt lgkmcnt(3)
	v_mfma_f32_16x16x32_bf16 v[106:109], v[202:205], v[220:223], v[182:185]
	s_waitcnt lgkmcnt(2)
	v_mfma_f32_16x16x32_bf16 v[102:105], v[216:219], v[220:223], v[186:189]
	s_waitcnt lgkmcnt(1)
	v_mfma_f32_16x16x32_bf16 v[98:101], v[212:215], v[220:223], v[126:129]
	s_waitcnt lgkmcnt(0)
	v_mfma_f32_16x16x32_bf16 v[126:129], v[236:239], v[220:223], v[154:157]
	s_nop 7
	s_setprio 0
	s_ashr_i32 s9, s4, 31
	s_add_u32 s8, s6, s4
	v_bfe_u32 v180, v170, 1, 5
	s_addc_u32 s9, s7, s9
	v_mul_lo_u32 v16, v174, s47
	v_and_b32_e32 v131, 16, v180
	s_mul_i32 s6, s9, 0x4800
	s_mul_hi_u32 s7, s8, 0x4800
	v_add3_u32 v16, 0, v131, v16
	v_and_b32_e32 v131, 8, v180
	s_add_i32 s7, s7, s6
	s_mul_i32 s6, s8, 0x4800
	v_add_u32_e32 v16, v16, v131
	s_add_u32 s6, s58, s6
	v_add_u32_e32 v179, 0x8800, v16
	s_addc_u32 s7, s59, s7
	s_lshl_b32 s10, s5, 7
	s_lshl_b32 s5, s5, 8
	v_lshlrev_b32_e32 v16, 3, v170
	v_cvt_pk_bf16_f32 v138, v138, v139
	v_cvt_pk_bf16_f32 v139, v140, v141
	v_cvt_pk_bf16_f32 v140, v142, v143
	v_cvt_pk_bf16_f32 v141, v144, v145
	s_add_u32 s6, s6, s5
	v_and_b32_e32 v16, 0x78, v16
	v_bfe_u32 v178, v170, 4, 2
	s_barrier
; __device__ __forceinline__ void retout_loop(ldsp lds, const bf16* proj, const bf16* st, bf16* mix, const float* ldr, int u0, int ustep, int nunits, int tid0) {
;     ...
;         store_acc_tile(TK, P, w, lane);
;         tile_put_frag(TS, R.sb, tid);
;         const bf16* gbase = proj + (row0 + 16 * w) * INW + C_RG + h * HDIM;
;         v4u gr[4];
; #pragma unroll
;         for (int k = 0; k < 4; ++k) { const int q = lane + 64 * k; gr[k] = *(const v4u*)(gbase + (size_t)(q >> 4) * INW + 8 * (q & 15)); }
;         const int unext = unit + ustep;
;         __syncthreads();
;         f32x4 acc[8]; zero8(acc);
;         mm128<false, false>(acc, TQ, TS, w, lane);
;         const float wf = __builtin_amdgcn_exp2f(l2f * (float)(i + 1)), wb = __builtin_amdgcn_exp2f(l2b * (float)(CHUNK - i));
; #pragma unroll
;         for (int c = 0; c < 8; ++c) acc[c] = acc[c] * wb + accF[c] * wf;
;         asm volatile("" ::: "memory");
;         if (unext < nunits) retout_fetch(R, proj, st, unext, tid);
	ds_write2_b64 v179, v[138:139], v[140:141] offset1:4
	v_cvt_pk_bf16_f32 v138, v146, v147
	v_cvt_pk_bf16_f32 v139, v148, v149
	v_cvt_pk_bf16_f32 v140, v150, v151
	v_cvt_pk_bf16_f32 v141, v152, v153
	v_cvt_pk_bf16_f32 v94, v94, v95
	v_cvt_pk_bf16_f32 v95, v96, v97
	v_cvt_pk_bf16_f32 v90, v90, v91
	v_cvt_pk_bf16_f32 v91, v92, v93
	v_cvt_pk_bf16_f32 v86, v86, v87
	v_cvt_pk_bf16_f32 v87, v88, v89
	v_cvt_pk_bf16_f32 v82, v82, v83
	v_cvt_pk_bf16_f32 v83, v84, v85
	s_addc_u32 s7, s7, 0
	v_lshlrev_b32_e32 v16, 1, v16
	v_mul_u32_u24_e32 v84, 0x2400, v178
	ds_write2_b64 v179, v[138:139], v[140:141] offset0:8 offset1:12
	ds_write2_b64 v179, v[94:95], v[90:91] offset0:16 offset1:20
	ds_write2_b64 v179, v[86:87], v[82:83] offset0:24 offset1:28
	ds_write_b128 v130, v[66:69]
	ds_write_b128 v132, v[70:73]
	ds_write_b128 v134, v[74:77]
	ds_write_b128 v136, v[78:81]
	v_lshl_add_u64 v[82:83], s[6:7], 0, v[16:17]
	v_lshlrev_b32_e32 v84, 1, v84
	v_mov_b32_e32 v85, v17
	v_lshl_add_u64 v[82:83], v[82:83], 0, v[84:85]
	s_movk_i32 s5, 0x2000
	v_add_co_u32_e32 v84, vcc, s5, v82
	s_mov_b32 s5, 0x14000
	s_nop 0
	v_addc_co_u32_e32 v85, vcc, 0, v83, vcc
	global_load_dwordx4 v[94:97], v[84:85], off offset:2048
	v_add_co_u32_e32 v84, vcc, s5, v82
	s_mov_b32 s5, 0x26000
	s_nop 0
	v_addc_co_u32_e32 v85, vcc, 0, v83, vcc
	global_load_dwordx4 v[90:93], v[84:85], off offset:2048
	v_add_co_u32_e32 v84, vcc, s5, v82
	s_mov_b32 s5, 0x38000
	s_nop 0
	v_addc_co_u32_e32 v85, vcc, 0, v83, vcc
	v_add_co_u32_e32 v82, vcc, s5, v82
	global_load_dwordx4 v[86:89], v[84:85], off offset:2048
	s_nop 0
	v_addc_co_u32_e32 v83, vcc, 0, v83, vcc
	global_load_dwordx4 v[82:85], v[82:83], off offset:2048
	s_waitcnt lgkmcnt(0)
	s_barrier
	s_setprio 1
	ds_read_b128 v[206:209], v176
	ds_read_b128 v[212:215], v158
	ds_read_b128 v[216:219], v158 offset:4352
	ds_read_b128 v[220:223], v158 offset:8704
	ds_read_b128 v[236:239], v158 offset:13056
	s_waitcnt lgkmcnt(3)
	v_mfma_f32_16x16x32_bf16 v[134:137], v[212:215], v[206:209], 0
	ds_read_b128 v[212:215], v158 offset:17408
	s_waitcnt lgkmcnt(3)
	v_mfma_f32_16x16x32_bf16 v[138:141], v[216:219], v[206:209], 0
	ds_read_b128 v[216:219], v158 offset:21760
	s_waitcnt lgkmcnt(3)
	v_mfma_f32_16x16x32_bf16 v[142:145], v[220:223], v[206:209], 0
	ds_read_b128 v[220:223], v158 offset:26112
	s_waitcnt lgkmcnt(3)
	v_mfma_f32_16x16x32_bf16 v[146:149], v[236:239], v[206:209], 0
	ds_read_b128 v[236:239], v158 offset:30464
	s_waitcnt lgkmcnt(3)
	v_mfma_f32_16x16x32_bf16 v[150:153], v[212:215], v[206:209], 0
	ds_read_b128 v[212:215], v176 offset:64
	s_waitcnt lgkmcnt(3)
	v_mfma_f32_16x16x32_bf16 v[154:157], v[216:219], v[206:209], 0
	ds_read_b128 v[216:219], v158 offset:64
	s_waitcnt lgkmcnt(3)
	v_mfma_f32_16x16x32_bf16 v[182:185], v[220:223], v[206:209], 0
	ds_read_b128 v[220:223], v158 offset:4416
	s_waitcnt lgkmcnt(3)
	v_mfma_f32_16x16x32_bf16 v[130:133], v[236:239], v[206:209], 0
	ds_read_b128 v[236:239], v158 offset:8768
	ds_read_b128 v[206:209], v158 offset:13120
	s_waitcnt lgkmcnt(3)
	v_mfma_f32_16x16x32_bf16 v[134:137], v[216:219], v[212:215], v[134:137]
	ds_read_b128 v[216:219], v158 offset:17472
	s_waitcnt lgkmcnt(3)
	v_mfma_f32_16x16x32_bf16 v[138:141], v[220:223], v[212:215], v[138:141]
	ds_read_b128 v[220:223], v158 offset:21824
	s_waitcnt lgkmcnt(3)
	v_mfma_f32_16x16x32_bf16 v[142:145], v[236:239], v[212:215], v[142:145]
	ds_read_b128 v[236:239], v158 offset:26176
	s_waitcnt lgkmcnt(3)
	v_mfma_f32_16x16x32_bf16 v[146:149], v[206:209], v[212:215], v[146:149]
	ds_read_b128 v[206:209], v158 offset:30528
	s_waitcnt lgkmcnt(3)
	v_mfma_f32_16x16x32_bf16 v[150:153], v[216:219], v[212:215], v[150:153]
	ds_read_b128 v[216:219], v176 offset:128
	s_waitcnt lgkmcnt(3)
	v_mfma_f32_16x16x32_bf16 v[154:157], v[220:223], v[212:215], v[154:157]
	ds_read_b128 v[220:223], v158 offset:128
	s_waitcnt lgkmcnt(3)
	v_mfma_f32_16x16x32_bf16 v[182:185], v[236:239], v[212:215], v[182:185]
	ds_read_b128 v[236:239], v158 offset:4480
	s_waitcnt lgkmcnt(3)
	v_mfma_f32_16x16x32_bf16 v[130:133], v[206:209], v[212:215], v[130:133]
	ds_read_b128 v[206:209], v158 offset:8832
	ds_read_b128 v[212:215], v158 offset:13184
	s_waitcnt lgkmcnt(3)
	v_mfma_f32_16x16x32_bf16 v[134:137], v[220:223], v[216:219], v[134:137]
	ds_read_b128 v[220:223], v158 offset:17536
	s_waitcnt lgkmcnt(3)
	v_mfma_f32_16x16x32_bf16 v[138:141], v[236:239], v[216:219], v[138:141]
	ds_read_b128 v[236:239], v158 offset:21888
	s_waitcnt lgkmcnt(3)
	v_mfma_f32_16x16x32_bf16 v[142:145], v[206:209], v[216:219], v[142:145]
	ds_read_b128 v[206:209], v158 offset:26240
	s_waitcnt lgkmcnt(3)
	v_mfma_f32_16x16x32_bf16 v[190:193], v[212:215], v[216:219], v[146:149]
	ds_read_b128 v[212:215], v158 offset:30592
	s_waitcnt lgkmcnt(3)
	v_mfma_f32_16x16x32_bf16 v[194:197], v[220:223], v[216:219], v[150:153]
	ds_read_b128 v[220:223], v176 offset:192
	s_waitcnt lgkmcnt(3)
	v_mfma_f32_16x16x32_bf16 v[198:201], v[236:239], v[216:219], v[154:157]
	ds_read_b128 v[236:239], v158 offset:192
	s_waitcnt lgkmcnt(3)
	v_mfma_f32_16x16x32_bf16 v[182:185], v[206:209], v[216:219], v[182:185]
	ds_read_b128 v[206:209], v158 offset:4544
	s_waitcnt lgkmcnt(3)
	v_mfma_f32_16x16x32_bf16 v[186:189], v[212:215], v[216:219], v[130:133]
	ds_read_b128 v[212:215], v158 offset:8896
	ds_read_b128 v[216:219], v158 offset:13248
	s_waitcnt lgkmcnt(3)
	v_mfma_f32_16x16x32_bf16 v[150:153], v[236:239], v[220:223], v[134:137]
	ds_read_b128 v[236:239], v158 offset:17600
	s_waitcnt lgkmcnt(3)
	v_mfma_f32_16x16x32_bf16 v[154:157], v[206:209], v[220:223], v[138:141]
	ds_read_b128 v[206:209], v158 offset:21952
	s_waitcnt lgkmcnt(3)
	v_mfma_f32_16x16x32_bf16 v[146:149], v[212:215], v[220:223], v[142:145]
	ds_read_b128 v[212:215], v158 offset:26304
	s_waitcnt lgkmcnt(3)
	v_mfma_f32_16x16x32_bf16 v[142:145], v[216:219], v[220:223], v[190:193]
	ds_read_b128 v[216:219], v158 offset:30656
	s_waitcnt lgkmcnt(3)
	v_mfma_f32_16x16x32_bf16 v[138:141], v[236:239], v[220:223], v[194:197]
	s_waitcnt lgkmcnt(2)
	v_mfma_f32_16x16x32_bf16 v[134:137], v[206:209], v[220:223], v[198:201]
	s_waitcnt lgkmcnt(1)
	v_mfma_f32_16x16x32_bf16 v[130:133], v[212:215], v[220:223], v[182:185]
	s_waitcnt lgkmcnt(0)
	v_mfma_f32_16x16x32_bf16 v[158:161], v[216:219], v[220:223], v[186:189]
	s_nop 7
	s_setprio 0
	s_add_i32 s1, s1, s95
	s_cmpk_gt_i32 s1, 0x3ff
	s_cselect_b64 s[6:7], -1, 0
	s_and_b64 vcc, exec, s[6:7]
	s_cbranch_vccnz .LBB0_461
; __device__ __forceinline__ void retout_fetch(RetoutRegs& R, const bf16* proj, const bf16* st, int unit, int tid) {
;     const int h = unit & 7, n = (unit >> 3) & 31, b = unit >> 8;
;     const bf16* base = proj + ((size_t)b * SEQ + (size_t)n * CHUNK) * INW + h * HDIM;
;     tile_fetch(R.q, base + C_RQ, INW, tid); tile_fetch(R.k, base + C_RK, INW, tid); tile_fetch(R.v, base + C_RV, INW, tid);
;     tile_fetch(R.sf, st + ((((size_t)0 * BATCH + b) * NRH + h) * NCH + n) * (size_t)(HDIM * HDIM), HDIM, tid);
;     tile_fetch(R.sb, st + ((((size_t)1 * BATCH + b) * NRH + h) * NCH + n) * (size_t)(HDIM * HDIM), HDIM, tid);
; }
	s_ashr_i32 s12, s1, 8
	s_bfe_u32 s11, s1, 0x50003
	s_ashr_i32 s13, s12, 31
	s_lshl_b64 s[16:17], s[12:13], 12
	s_lshl_b32 s18, s11, 7
	s_or_b32 s16, s18, s16
	s_mulk_i32 s17, 0x4800
	s_mul_hi_u32 s18, s16, 0x4800
	s_and_b32 s5, s1, 7
	s_add_i32 s18, s18, s17
	s_mulk_i32 s16, 0x4800
	s_add_u32 s16, s58, s16
	s_addc_u32 s17, s59, s18
	s_lshl_b32 s18, s5, 8
	s_add_u32 s16, s16, s18
	s_addc_u32 s17, s17, 0
	v_lshl_add_u64 v[34:35], s[16:17], 0, v[16:17]
	s_mov_b64 s[16:17], 0x1000
	v_lshl_add_u64 v[8:9], v[34:35], 0, s[16:17]
	v_lshl_add_u64 v[26:27], v[34:35], 0, s[48:49]
	v_lshl_add_u64 v[42:43], v[34:35], 0, s[30:31]
	v_mad_i64_i32 v[0:1], s[16:17], v162, s85, v[8:9]
	v_mad_i64_i32 v[4:5], s[16:17], v164, s85, v[8:9]
	v_mad_i64_i32 v[10:11], s[16:17], v166, s85, v[8:9]
	v_mad_i64_i32 v[12:13], s[16:17], v168, s85, v[8:9]
	v_mad_i64_i32 v[18:19], s[16:17], v162, s85, v[26:27]
	v_mad_i64_i32 v[22:23], s[16:17], v164, s85, v[26:27]
	v_mad_i64_i32 v[28:29], s[16:17], v166, s85, v[26:27]
	v_mad_i64_i32 v[30:31], s[16:17], v168, s85, v[26:27]
	v_mad_i64_i32 v[34:35], s[16:17], v162, s85, v[42:43]
	v_mad_i64_i32 v[38:39], s[16:17], v164, s85, v[42:43]
	v_mad_i64_i32 v[44:45], s[16:17], v166, s85, v[42:43]
	v_mad_i64_i32 v[46:47], s[16:17], v168, s85, v[42:43]
	s_lshl_b64 s[16:17], s[12:13], 8
	s_lshl_b32 s18, s5, 5
	s_or_b32 s16, s16, s18
	s_or_b32 s16, s16, s11
	s_lshl_b64 s[16:17], s[16:17], 15
	s_add_u32 s16, s62, s16
	s_addc_u32 s17, s63, s17
	s_lshl_b64 s[12:13], s[12:13], 23
	s_lshl_b32 s5, s5, 20
	s_or_b32 s5, s12, s5
	s_add_u32 s5, s62, s5
	s_addc_u32 s13, s63, s13
	s_lshl_b32 s11, s11, 15
	s_add_u32 s12, s5, s11
	s_addc_u32 s13, s13, 0
	v_ashrrev_i32_e32 v163, 31, v162
	v_ashrrev_i32_e32 v165, 31, v164
	v_ashrrev_i32_e32 v167, 31, v166
	v_ashrrev_i32_e32 v169, 31, v168
	v_lshl_add_u64 v[70:71], s[12:13], 0, v[16:17]
	s_mov_b64 s[12:13], 0x2000000
	v_lshl_add_u64 v[58:59], s[16:17], 0, v[16:17]
	v_lshlrev_b64 v[66:67], 8, v[162:163]
	v_lshlrev_b64 v[68:69], 8, v[164:165]
	v_lshlrev_b64 v[74:75], 8, v[166:167]
	v_lshlrev_b64 v[76:77], 8, v[168:169]
	v_lshl_add_u64 v[78:79], v[70:71], 0, s[12:13]
	v_lshl_add_u64 v[50:51], v[58:59], 0, v[66:67]
	v_lshl_add_u64 v[54:55], v[58:59], 0, v[68:69]
	v_lshl_add_u64 v[60:61], v[58:59], 0, v[74:75]
	v_lshl_add_u64 v[62:63], v[58:59], 0, v[76:77]
	v_lshl_add_u64 v[66:67], v[78:79], 0, v[66:67]
	v_lshl_add_u64 v[70:71], v[78:79], 0, v[68:69]
	v_lshl_add_u64 v[74:75], v[78:79], 0, v[74:75]
	v_lshl_add_u64 v[78:79], v[78:79], 0, v[76:77]
	global_load_dwordx4 v[0:3], v[0:1], off
	s_nop 0
	global_load_dwordx4 v[4:7], v[4:5], off
	s_nop 0
	global_load_dwordx4 v[8:11], v[10:11], off
	s_nop 0
	global_load_dwordx4 v[12:15], v[12:13], off
	s_nop 0
	global_load_dwordx4 v[18:21], v[18:19], off
	s_nop 0
	global_load_dwordx4 v[22:25], v[22:23], off
	s_nop 0
	global_load_dwordx4 v[26:29], v[28:29], off
	s_nop 0
	global_load_dwordx4 v[30:33], v[30:31], off
	s_nop 0
	global_load_dwordx4 v[34:37], v[34:35], off
	s_nop 0
	global_load_dwordx4 v[38:41], v[38:39], off
	s_nop 0
	global_load_dwordx4 v[42:45], v[44:45], off
	s_nop 0
	global_load_dwordx4 v[46:49], v[46:47], off
	s_nop 0
	global_load_dwordx4 v[50:53], v[50:51], off
	s_nop 0
	global_load_dwordx4 v[54:57], v[54:55], off
	s_nop 0
	global_load_dwordx4 v[58:61], v[60:61], off
	s_nop 0
	global_load_dwordx4 v[62:65], v[62:63], off
	s_nop 0
	global_load_dwordx4 v[66:69], v[66:67], off
	s_nop 0
	global_load_dwordx4 v[70:73], v[70:71], off
	s_nop 0
	global_load_dwordx4 v[74:77], v[74:75], off
	s_nop 0
	global_load_dwordx4 v[78:81], v[78:79], off
	s_branch .LBB0_461
